# dense attention: ring of 6 LDS tiles, one workgroup barrier per two key tiles
# speedup vs baseline: 1.0306x; 1.0041x over previous
.LBB0_301:
	s_add_i32 s30, s27, s19
	s_cmpk_gt_i32 s30, 0x1ff
	s_mov_b64 s[12:13], -1
	s_cbranch_scc1 .LBB0_300
	s_ashr_i32 s28, s30, 8
	s_and_b32 s31, s26, 0x80
	s_mul_i32 s13, s28, 0x6000000
	s_mul_hi_i32 s12, s28, 0x6000000
	s_add_u32 s33, s37, s13
	s_addc_u32 s35, s40, s12
	s_lshl_b32 s12, s30, 1
	s_and_b32 s29, s12, 0x1c0
	s_lshl_b32 s12, s29, 1
	s_add_u32 s12, s33, s12
	s_addc_u32 s13, s35, 0
	s_and_b32 s34, s30, 0x80
	s_add_u32 s34, s33, s34
	s_addc_u32 s35, s35, 0
	s_lshl_b32 s30, s30, 9
	v_mov_b32_e32 v14, v0
	s_and_b32 s30, s30, 0x3e00
	v_mov_b32_e32 v11, v171
	v_readfirstlane_b32 s33, v14
	s_andn2_b32 s33, s33, 63
	v_and_or_b32 v2, v14, 31, s30
	v_bfe_u32 v15, v14, 5, 1
	v_add_u32_e32 v172, s33, v2
	v_mov_b64_e32 v[2:3], s[12:13]
	v_mad_i64_i32 v[2:3], s[12:13], v172, s20, v[2:3]
	v_lshlrev_b32_e32 v170, 4, v15
	v_lshl_add_u64 v[2:3], v[2:3], 0, v[170:171]
	v_lshl_add_u64 v[4:5], v[2:3], 0, s[6:7]
	v_add_co_u32_e32 v6, vcc, s21, v2
	v_ashrrev_i32_e32 v16, 3, v14
	s_nop 0
	v_addc_co_u32_e32 v7, vcc, 0, v3, vcc
	global_load_dwordx4 v[130:133], v[2:3], off
	global_load_dwordx4 v[134:137], v[2:3], off offset:32
	global_load_dwordx4 v[138:141], v[4:5], off offset:32
	global_load_dwordx4 v[142:145], v[4:5], off offset:64
	global_load_dwordx4 v[146:149], v[2:3], off offset:64
	global_load_dwordx4 v[150:153], v[2:3], off offset:96
	global_load_dwordx4 v[154:157], v[6:7], off
	global_load_dwordx4 v[158:161], v[4:5], off offset:96
	v_mov_b64_e32 v[2:3], s[34:35]
	v_lshlrev_b32_e32 v4, 4, v14
	v_mad_i64_i32 v[2:3], s[12:13], v16, s20, v[2:3]
	v_and_b32_e32 v10, 0x70, v4
	v_lshl_add_u64 v[12:13], v[2:3], 0, v[10:11]
	global_load_dwordx4 v[2:5], v[12:13], off offset:1024
	global_load_dwordx4 v[6:9], v[12:13], off offset:1280
	v_add_co_u32_e32 v12, vcc, s23, v12
	s_waitcnt lgkmcnt(0)
	s_nop 0
	v_addc_co_u32_e32 v13, vcc, 0, v13, vcc
	s_barrier
	global_load_dwordx4 v[162:165], v[12:13], off offset:1024
	global_load_dwordx4 v[166:169], v[12:13], off offset:1280
	v_lshlrev_b32_e32 v12, 1, v14
	v_lshrrev_b32_e32 v13, 1, v14
	v_lshlrev_b32_e32 v174, 3, v15
	v_and_b32_e32 v15, 8, v12
	v_and_b32_e32 v18, 4, v13
	v_and_b32_e32 v173, 32, v12
	v_mad_i64_i32 v[12:13], s[12:13], v16, s20, 0
	v_and_b32_e32 v11, 19, v14
	v_lshrrev_b32_e32 v17, 2, v14
	v_lshlrev_b32_e32 v14, 3, v14
	v_mul_lo_u32 v19, v16, s22
	v_mad_i64_i32 v[12:13], s[12:13], s28, v1, v[12:13]
	v_mov_b32_e32 v50, 0
	v_and_b32_e32 v175, 24, v14
	v_or3_b32 v11, v11, v15, v18
	v_and_or_b32 v14, v17, 3, v174
	v_add3_u32 v180, 0, v19, v10
	v_or3_b32 v12, v12, s31, v10
	s_mov_b32 s33, 0
	s_mov_b32 s30, 0
	v_mov_b32_e32 v51, v50
	v_mov_b32_e32 v52, v50
	v_mov_b32_e32 v53, v50
	v_mov_b32_e32 v54, v50
	v_mov_b32_e32 v55, v50
	v_mov_b32_e32 v56, v50
	v_mov_b32_e32 v57, v50
	v_mov_b32_e32 v58, v50
	v_mul_u32_u24_e32 v181, 0x90, v11
	v_mul_u32_u24_e32 v182, 0x90, v14
	v_lshl_add_u64 v[176:177], s[4:5], 0, v[12:13]
	v_mov_b32_e32 v59, v50
	v_mov_b32_e32 v60, v50
	v_mov_b32_e32 v61, v50
	v_mov_b32_e32 v62, v50
	v_mov_b32_e32 v63, v50
	v_mov_b32_e32 v64, v50
	v_mov_b32_e32 v65, v50
	v_mov_b32_e32 v34, v50
	v_mov_b32_e32 v35, v50
	v_mov_b32_e32 v36, v50
	v_mov_b32_e32 v37, v50
	v_mov_b32_e32 v38, v50
	v_mov_b32_e32 v39, v50
	v_mov_b32_e32 v40, v50
	v_mov_b32_e32 v41, v50
	v_mov_b32_e32 v42, v50
	v_mov_b32_e32 v43, v50
	s_waitcnt vmcnt(3)
	ds_write_b128 v180, v[2:5]
	s_waitcnt vmcnt(2)
	ds_write_b128 v180, v[6:9] offset:9216
	s_waitcnt vmcnt(1)
	ds_write_b128 v180, v[162:165] offset:18432
	s_waitcnt vmcnt(0)
	ds_write_b128 v180, v[166:169] offset:27648
	v_mov_b32_e32 v44, v50
	v_mov_b32_e32 v45, v50
	v_mov_b32_e32 v46, v50
	v_mov_b32_e32 v47, v50
	v_mov_b32_e32 v48, v50
	v_mov_b32_e32 v49, v50
	v_mov_b32_e32 v2, v50
	v_mov_b32_e32 v3, v50
	v_mov_b32_e32 v4, v50
	v_mov_b32_e32 v5, v50
	v_mov_b32_e32 v6, v50
	v_mov_b32_e32 v7, v50
	v_mov_b32_e32 v8, v50
	v_mov_b32_e32 v9, v50
	v_mov_b32_e32 v10, v50
	v_mov_b32_e32 v11, v50
	v_mov_b32_e32 v12, v50
	v_mov_b32_e32 v13, v50
	v_mov_b32_e32 v14, v50
	v_mov_b32_e32 v15, v50
	v_mov_b32_e32 v16, v50
	v_mov_b32_e32 v17, v50
	v_mov_b32_e32 v18, v50
	v_mov_b32_e32 v19, v50
	v_mov_b32_e32 v20, v50
	v_mov_b32_e32 v21, v50
	v_mov_b32_e32 v22, v50
	v_mov_b32_e32 v23, v50
	v_mov_b32_e32 v24, v50
	v_mov_b32_e32 v25, v50
	v_mov_b32_e32 v26, v50
	v_mov_b32_e32 v27, v50
	v_mov_b32_e32 v28, v50
	v_mov_b32_e32 v29, v50
	v_mov_b32_e32 v30, v50
	v_mov_b32_e32 v31, v50
	v_mov_b32_e32 v32, v50
	v_mov_b32_e32 v33, v50
	v_mov_b32_e32 v178, v50
	v_mov_b32_e32 v179, v50
	v_mov_b32_e32 v218, 0
	v_mov_b32_e32 v219, 0
	v_mov_b32_e32 v220, 0
	v_mov_b32_e32 v221, 0
	v_mov_b32_e32 v222, 0
	v_mov_b32_e32 v223, 0
	v_mov_b32_e32 v208, 0
	v_mov_b32_e32 v209, 0
	v_mov_b32_e32 v210, 0
	v_mov_b32_e32 v211, 0
	v_mov_b32_e32 v212, 0
	v_mov_b32_e32 v213, 0
	v_mov_b32_e32 v214, 0
	v_mov_b32_e32 v215, 0
	v_mov_b32_e32 v106, 0
	v_mov_b32_e32 v107, 0
	v_mov_b32_e32 v108, 0
	v_mov_b32_e32 v109, 0
	v_mov_b32_e32 v122, 0
	v_mov_b32_e32 v123, 0
	v_mov_b32_e32 v124, 0
	v_mov_b32_e32 v125, 0
	global_load_dwordx4 v[162:165], v[176:177], off
	global_load_dwordx4 v[166:169], v[176:177], off offset:256
	v_add_u32_e32 v183, v181, v170
	v_add3_u32 v216, v182, v173, v175
	v_add_u32_e32 v226, 0xd800, v183
	v_add_u32_e32 v227, 0xd800, v216
	v_add_u32_e32 v228, 0xd800, v180
	v_lshl_add_u64 v[176:177], v[176:177], 0, s[8:9]
	s_waitcnt vmcnt(0)
	ds_write_b128 v180, v[162:165] offset:36864
	ds_write_b128 v180, v[166:169] offset:46080
	s_waitcnt lgkmcnt(0)
	s_barrier
	ds_read_b128 v[184:187], v183
	ds_read_b128 v[188:191], v183 offset:32
	ds_read_b128 v[192:195], v183 offset:64
	ds_read_b128 v[196:199], v183 offset:96
	s_waitcnt lgkmcnt(3)
	v_mfma_f32_32x32x16_bf16 v[66:81], v[184:187], v[130:133], 0
	s_waitcnt lgkmcnt(2)
	v_mfma_f32_32x32x16_bf16 v[66:81], v[188:191], v[134:137], v[66:81]
	s_waitcnt lgkmcnt(1)
	v_mfma_f32_32x32x16_bf16 v[66:81], v[192:195], v[146:149], v[66:81]
	s_waitcnt lgkmcnt(0)
	v_mfma_f32_32x32x16_bf16 v[66:81], v[196:199], v[150:153], v[66:81]
	v_mfma_f32_32x32x16_bf16 v[82:97], v[184:187], v[154:157], 0
	v_mfma_f32_32x32x16_bf16 v[82:97], v[188:191], v[138:141], v[82:97]
	v_mfma_f32_32x32x16_bf16 v[82:97], v[192:195], v[142:145], v[82:97]
	v_mfma_f32_32x32x16_bf16 v[82:97], v[196:199], v[158:161], v[82:97]
	s_branch .Lat_enter

.Lat_enter:
	global_load_dwordx4 v[162:165], v[176:177], off
	global_load_dwordx4 v[166:169], v[176:177], off offset:256
	ds_read_b128 v[184:187], v183 offset:4608
	ds_read_b128 v[188:191], v183 offset:4640
	ds_read_b128 v[192:195], v183 offset:4672
	ds_read_b128 v[196:199], v183 offset:4704
	v_exp_f32_e32 v66, v66
	v_exp_f32_e32 v67, v67
	v_add_f32_e32 v178, v178, v66
	v_add_f32_e32 v218, v218, v67
	v_cvt_pk_bf16_f32 v66, v66, v67
	v_mfma_f32_32x32x16_bf16 v[50:65], v[208:211], v[106:109], v[50:65]
	v_exp_f32_e32 v68, v68
	v_exp_f32_e32 v69, v69
	v_add_f32_e32 v219, v219, v68
	v_add_f32_e32 v220, v220, v69
	v_cvt_pk_bf16_f32 v67, v68, v69
	v_mfma_f32_32x32x16_bf16 v[34:49], v[212:215], v[106:109], v[34:49]
	v_lshl_add_u64 v[176:177], v[176:177], 0, s[8:9]
	v_exp_f32_e32 v70, v70
	v_exp_f32_e32 v71, v71
	v_add_f32_e32 v178, v178, v70
	v_add_f32_e32 v218, v218, v71
	v_cvt_pk_bf16_f32 v68, v70, v71
	v_mfma_f32_32x32x16_bf16 v[18:33], v[208:211], v[122:125], v[18:33]
	v_exp_f32_e32 v72, v72
	v_exp_f32_e32 v73, v73
	v_add_f32_e32 v219, v219, v72
	v_add_f32_e32 v220, v220, v73
	v_cvt_pk_bf16_f32 v69, v72, v73
	v_mfma_f32_32x32x16_bf16 v[2:17], v[212:215], v[122:125], v[2:17]
	v_exp_f32_e32 v82, v82
	v_exp_f32_e32 v83, v83
	v_add_f32_e32 v179, v179, v82
	v_add_f32_e32 v221, v221, v83
	v_cvt_pk_bf16_f32 v82, v82, v83
	s_waitcnt lgkmcnt(0)
	v_mfma_f32_32x32x16_bf16 v[98:113], v[184:187], v[130:133], 0
	ds_read_b64_tr_b16 v[200:201], v216 offset:9216
	ds_read_b64_tr_b16 v[202:203], v216 offset:9792
	ds_read_b64_tr_b16 v[204:205], v216 offset:9280
	ds_read_b64_tr_b16 v[206:207], v216 offset:9856
	v_exp_f32_e32 v84, v84
	v_exp_f32_e32 v85, v85
	v_add_f32_e32 v222, v222, v84
	v_add_f32_e32 v223, v223, v85
	v_cvt_pk_bf16_f32 v83, v84, v85
	v_mfma_f32_32x32x16_bf16 v[98:113], v[188:191], v[134:137], v[98:113]
	ds_read_b64_tr_b16 v[208:209], v216 offset:11520
	ds_read_b64_tr_b16 v[210:211], v216 offset:12096
	ds_read_b64_tr_b16 v[212:213], v216 offset:11584
	ds_read_b64_tr_b16 v[214:215], v216 offset:12160
	v_exp_f32_e32 v86, v86
	v_exp_f32_e32 v87, v87
	v_add_f32_e32 v179, v179, v86
	v_add_f32_e32 v221, v221, v87
	v_cvt_pk_bf16_f32 v84, v86, v87
	v_mfma_f32_32x32x16_bf16 v[98:113], v[192:195], v[146:149], v[98:113]
	v_exp_f32_e32 v88, v88
	v_exp_f32_e32 v89, v89
	v_add_f32_e32 v222, v222, v88
	v_add_f32_e32 v223, v223, v89
	v_cvt_pk_bf16_f32 v85, v88, v89
	v_mfma_f32_32x32x16_bf16 v[98:113], v[196:199], v[150:153], v[98:113]
	v_exp_f32_e32 v74, v74
	v_exp_f32_e32 v75, v75
	v_add_f32_e32 v178, v178, v74
	v_add_f32_e32 v218, v218, v75
	v_cvt_pk_bf16_f32 v74, v74, v75
	v_mfma_f32_32x32x16_bf16 v[114:129], v[184:187], v[154:157], 0
	v_exp_f32_e32 v76, v76
	v_exp_f32_e32 v77, v77
	v_add_f32_e32 v219, v219, v76
	v_add_f32_e32 v220, v220, v77
	v_cvt_pk_bf16_f32 v75, v76, v77
	v_mfma_f32_32x32x16_bf16 v[114:129], v[188:191], v[138:141], v[114:129]
	v_exp_f32_e32 v78, v78
	v_exp_f32_e32 v79, v79
	v_add_f32_e32 v178, v178, v78
	v_add_f32_e32 v218, v218, v79
	v_cvt_pk_bf16_f32 v76, v78, v79
	v_mfma_f32_32x32x16_bf16 v[114:129], v[192:195], v[142:145], v[114:129]
	v_exp_f32_e32 v80, v80
	v_exp_f32_e32 v81, v81
	v_add_f32_e32 v219, v219, v80
	v_add_f32_e32 v220, v220, v81
	v_cvt_pk_bf16_f32 v77, v80, v81
	v_mfma_f32_32x32x16_bf16 v[114:129], v[196:199], v[158:161], v[114:129]
	v_exp_f32_e32 v90, v90
	v_exp_f32_e32 v91, v91
	v_add_f32_e32 v179, v179, v90
	v_add_f32_e32 v221, v221, v91
	v_cvt_pk_bf16_f32 v90, v90, v91
	s_waitcnt lgkmcnt(4)
	v_mfma_f32_32x32x16_bf16 v[50:65], v[200:203], v[66:69], v[50:65]
	ds_read_b128 v[184:187], v183 offset:18432
	ds_read_b128 v[188:191], v183 offset:18464
	ds_read_b128 v[192:195], v183 offset:18496
	ds_read_b128 v[196:199], v183 offset:18528
	v_exp_f32_e32 v92, v92
	v_exp_f32_e32 v93, v93
	v_add_f32_e32 v222, v222, v92
	v_add_f32_e32 v223, v223, v93
	v_cvt_pk_bf16_f32 v91, v92, v93
	v_mfma_f32_32x32x16_bf16 v[34:49], v[204:207], v[66:69], v[34:49]
	v_exp_f32_e32 v94, v94
	v_exp_f32_e32 v95, v95
	v_add_f32_e32 v179, v179, v94
	v_add_f32_e32 v221, v221, v95
	v_cvt_pk_bf16_f32 v92, v94, v95
	v_mfma_f32_32x32x16_bf16 v[18:33], v[200:203], v[82:85], v[18:33]
	v_exp_f32_e32 v96, v96
	v_exp_f32_e32 v97, v97
	v_add_f32_e32 v222, v222, v96
	v_add_f32_e32 v223, v223, v97
	v_cvt_pk_bf16_f32 v93, v96, v97
	v_mfma_f32_32x32x16_bf16 v[2:17], v[204:207], v[82:85], v[2:17]
	v_exp_f32_e32 v98, v98
	v_exp_f32_e32 v99, v99
	v_add_f32_e32 v178, v178, v98
	v_add_f32_e32 v218, v218, v99
	v_cvt_pk_bf16_f32 v98, v98, v99
	s_waitcnt lgkmcnt(4)
	v_mfma_f32_32x32x16_bf16 v[50:65], v[208:211], v[74:77], v[50:65]
	ds_read_b64_tr_b16 v[200:201], v216 offset:13824
	ds_read_b64_tr_b16 v[202:203], v216 offset:14400
	ds_read_b64_tr_b16 v[204:205], v216 offset:13888
	ds_read_b64_tr_b16 v[206:207], v216 offset:14464
	v_exp_f32_e32 v100, v100
	v_exp_f32_e32 v101, v101
	v_add_f32_e32 v219, v219, v100
	v_add_f32_e32 v220, v220, v101
	v_cvt_pk_bf16_f32 v99, v100, v101
	v_mfma_f32_32x32x16_bf16 v[34:49], v[212:215], v[74:77], v[34:49]
	v_exp_f32_e32 v102, v102
	v_exp_f32_e32 v103, v103
	v_add_f32_e32 v178, v178, v102
	v_add_f32_e32 v218, v218, v103
	v_cvt_pk_bf16_f32 v100, v102, v103
	v_mfma_f32_32x32x16_bf16 v[18:33], v[208:211], v[90:93], v[18:33]
	v_exp_f32_e32 v104, v104
	v_exp_f32_e32 v105, v105
	v_add_f32_e32 v219, v219, v104
	v_add_f32_e32 v220, v220, v105
	v_cvt_pk_bf16_f32 v101, v104, v105
	v_mfma_f32_32x32x16_bf16 v[2:17], v[212:215], v[90:93], v[2:17]
	v_exp_f32_e32 v114, v114
	v_exp_f32_e32 v115, v115
	v_add_f32_e32 v179, v179, v114
	v_add_f32_e32 v221, v221, v115
	v_cvt_pk_bf16_f32 v114, v114, v115
	s_waitcnt lgkmcnt(4)
	v_mfma_f32_32x32x16_bf16 v[66:81], v[184:187], v[130:133], 0
	ds_read_b64_tr_b16 v[208:209], v216 offset:16128
	ds_read_b64_tr_b16 v[210:211], v216 offset:16704
	ds_read_b64_tr_b16 v[212:213], v216 offset:16192
	ds_read_b64_tr_b16 v[214:215], v216 offset:16768
	v_exp_f32_e32 v116, v116
	v_exp_f32_e32 v117, v117
	v_add_f32_e32 v222, v222, v116
	v_add_f32_e32 v223, v223, v117
	v_cvt_pk_bf16_f32 v115, v116, v117
	v_mfma_f32_32x32x16_bf16 v[66:81], v[188:191], v[134:137], v[66:81]
	v_exp_f32_e32 v118, v118
	v_exp_f32_e32 v119, v119
	v_add_f32_e32 v179, v179, v118
	v_add_f32_e32 v221, v221, v119
	v_cvt_pk_bf16_f32 v116, v118, v119
	v_mfma_f32_32x32x16_bf16 v[66:81], v[192:195], v[146:149], v[66:81]
	v_exp_f32_e32 v120, v120
	v_exp_f32_e32 v121, v121
	v_add_f32_e32 v222, v222, v120
	v_add_f32_e32 v223, v223, v121
	v_cvt_pk_bf16_f32 v117, v120, v121
	v_mfma_f32_32x32x16_bf16 v[66:81], v[196:199], v[150:153], v[66:81]
	v_exp_f32_e32 v106, v106
	v_exp_f32_e32 v107, v107
	v_add_f32_e32 v178, v178, v106
	v_add_f32_e32 v218, v218, v107
	v_cvt_pk_bf16_f32 v106, v106, v107
	s_waitcnt lgkmcnt(4)
	v_mfma_f32_32x32x16_bf16 v[50:65], v[200:203], v[98:101], v[50:65]
	v_exp_f32_e32 v108, v108
	v_exp_f32_e32 v109, v109
	v_add_f32_e32 v219, v219, v108
	v_add_f32_e32 v220, v220, v109
	v_cvt_pk_bf16_f32 v107, v108, v109
	v_mfma_f32_32x32x16_bf16 v[34:49], v[204:207], v[98:101], v[34:49]
	v_exp_f32_e32 v110, v110
	v_exp_f32_e32 v111, v111
	v_add_f32_e32 v178, v178, v110
	v_add_f32_e32 v218, v218, v111
	v_cvt_pk_bf16_f32 v108, v110, v111
	v_mfma_f32_32x32x16_bf16 v[18:33], v[200:203], v[114:117], v[18:33]
	s_waitcnt vmcnt(0)
	ds_write_b128 v228, v[162:165]
	ds_write_b128 v228, v[166:169] offset:9216
	v_exp_f32_e32 v112, v112
	v_exp_f32_e32 v113, v113
	v_add_f32_e32 v219, v219, v112
	v_add_f32_e32 v220, v220, v113
	v_cvt_pk_bf16_f32 v109, v112, v113
	v_mfma_f32_32x32x16_bf16 v[2:17], v[204:207], v[114:117], v[2:17]
	v_exp_f32_e32 v122, v122
	v_exp_f32_e32 v123, v123
	v_add_f32_e32 v179, v179, v122
	v_add_f32_e32 v221, v221, v123
	v_cvt_pk_bf16_f32 v122, v122, v123
	v_mfma_f32_32x32x16_bf16 v[82:97], v[184:187], v[154:157], 0
	v_exp_f32_e32 v124, v124
	v_exp_f32_e32 v125, v125
	v_add_f32_e32 v222, v222, v124
	v_add_f32_e32 v223, v223, v125
	v_cvt_pk_bf16_f32 v123, v124, v125
	v_mfma_f32_32x32x16_bf16 v[82:97], v[188:191], v[138:141], v[82:97]
	v_exp_f32_e32 v126, v126
	v_exp_f32_e32 v127, v127
	v_add_f32_e32 v179, v179, v126
	v_add_f32_e32 v221, v221, v127
	v_cvt_pk_bf16_f32 v124, v126, v127
	v_mfma_f32_32x32x16_bf16 v[82:97], v[192:195], v[142:145], v[82:97]
	v_exp_f32_e32 v128, v128
	v_exp_f32_e32 v129, v129
	v_add_f32_e32 v222, v222, v128
	v_add_f32_e32 v223, v223, v129
	v_cvt_pk_bf16_f32 v125, v128, v129
	v_mfma_f32_32x32x16_bf16 v[82:97], v[196:199], v[158:161], v[82:97]
	global_load_dwordx4 v[162:165], v[176:177], off
	global_load_dwordx4 v[166:169], v[176:177], off offset:256
	ds_read_b128 v[184:187], v183 offset:23040
	ds_read_b128 v[188:191], v183 offset:23072
	ds_read_b128 v[192:195], v183 offset:23104
	ds_read_b128 v[196:199], v183 offset:23136
	v_exp_f32_e32 v66, v66
	v_exp_f32_e32 v67, v67
	v_add_f32_e32 v178, v178, v66
	v_add_f32_e32 v218, v218, v67
	v_cvt_pk_bf16_f32 v66, v66, v67
	s_waitcnt lgkmcnt(6)
	v_mfma_f32_32x32x16_bf16 v[50:65], v[208:211], v[106:109], v[50:65]
	v_exp_f32_e32 v68, v68
	v_exp_f32_e32 v69, v69
	v_add_f32_e32 v219, v219, v68
	v_add_f32_e32 v220, v220, v69
	v_cvt_pk_bf16_f32 v67, v68, v69
	v_mfma_f32_32x32x16_bf16 v[34:49], v[212:215], v[106:109], v[34:49]
	v_lshl_add_u64 v[176:177], v[176:177], 0, s[8:9]
	v_exp_f32_e32 v70, v70
	v_exp_f32_e32 v71, v71
	v_add_f32_e32 v178, v178, v70
	v_add_f32_e32 v218, v218, v71
	v_cvt_pk_bf16_f32 v68, v70, v71
	v_mfma_f32_32x32x16_bf16 v[18:33], v[208:211], v[122:125], v[18:33]
	v_exp_f32_e32 v72, v72
	v_exp_f32_e32 v73, v73
	v_add_f32_e32 v219, v219, v72
	v_add_f32_e32 v220, v220, v73
	v_cvt_pk_bf16_f32 v69, v72, v73
	v_mfma_f32_32x32x16_bf16 v[2:17], v[212:215], v[122:125], v[2:17]
	v_exp_f32_e32 v82, v82
	v_exp_f32_e32 v83, v83
	v_add_f32_e32 v179, v179, v82
	v_add_f32_e32 v221, v221, v83
	v_cvt_pk_bf16_f32 v82, v82, v83
	s_waitcnt lgkmcnt(0)
	v_mfma_f32_32x32x16_bf16 v[98:113], v[184:187], v[130:133], 0
	ds_read_b64_tr_b16 v[200:201], v216 offset:27648
	ds_read_b64_tr_b16 v[202:203], v216 offset:28224
	ds_read_b64_tr_b16 v[204:205], v216 offset:27712
	ds_read_b64_tr_b16 v[206:207], v216 offset:28288
	v_exp_f32_e32 v84, v84
	v_exp_f32_e32 v85, v85
	v_add_f32_e32 v222, v222, v84
	v_add_f32_e32 v223, v223, v85
	v_cvt_pk_bf16_f32 v83, v84, v85
	v_mfma_f32_32x32x16_bf16 v[98:113], v[188:191], v[134:137], v[98:113]
	ds_read_b64_tr_b16 v[208:209], v216 offset:29952
	ds_read_b64_tr_b16 v[210:211], v216 offset:30528
	ds_read_b64_tr_b16 v[212:213], v216 offset:30016
	ds_read_b64_tr_b16 v[214:215], v216 offset:30592
	v_exp_f32_e32 v86, v86
	v_exp_f32_e32 v87, v87
	v_add_f32_e32 v179, v179, v86
	v_add_f32_e32 v221, v221, v87
	v_cvt_pk_bf16_f32 v84, v86, v87
	v_mfma_f32_32x32x16_bf16 v[98:113], v[192:195], v[146:149], v[98:113]
	v_exp_f32_e32 v88, v88
	v_exp_f32_e32 v89, v89
	v_add_f32_e32 v222, v222, v88
	v_add_f32_e32 v223, v223, v89
	v_cvt_pk_bf16_f32 v85, v88, v89
	v_mfma_f32_32x32x16_bf16 v[98:113], v[196:199], v[150:153], v[98:113]
	v_exp_f32_e32 v74, v74
	v_exp_f32_e32 v75, v75
	v_add_f32_e32 v178, v178, v74
	v_add_f32_e32 v218, v218, v75
	v_cvt_pk_bf16_f32 v74, v74, v75
	v_mfma_f32_32x32x16_bf16 v[114:129], v[184:187], v[154:157], 0
	v_exp_f32_e32 v76, v76
	v_exp_f32_e32 v77, v77
	v_add_f32_e32 v219, v219, v76
	v_add_f32_e32 v220, v220, v77
	v_cvt_pk_bf16_f32 v75, v76, v77
	v_mfma_f32_32x32x16_bf16 v[114:129], v[188:191], v[138:141], v[114:129]
	v_exp_f32_e32 v78, v78
	v_exp_f32_e32 v79, v79
	v_add_f32_e32 v178, v178, v78
	v_add_f32_e32 v218, v218, v79
	v_cvt_pk_bf16_f32 v76, v78, v79
	v_mfma_f32_32x32x16_bf16 v[114:129], v[192:195], v[142:145], v[114:129]
	v_exp_f32_e32 v80, v80
	v_exp_f32_e32 v81, v81
	v_add_f32_e32 v219, v219, v80
	v_add_f32_e32 v220, v220, v81
	v_cvt_pk_bf16_f32 v77, v80, v81
	v_mfma_f32_32x32x16_bf16 v[114:129], v[196:199], v[158:161], v[114:129]
	v_exp_f32_e32 v90, v90
	v_exp_f32_e32 v91, v91
	v_add_f32_e32 v179, v179, v90
	v_add_f32_e32 v221, v221, v91
	v_cvt_pk_bf16_f32 v90, v90, v91
	s_waitcnt lgkmcnt(4)
	v_mfma_f32_32x32x16_bf16 v[50:65], v[200:203], v[66:69], v[50:65]
	ds_read_b128 v[184:187], v183 offset:36864
	ds_read_b128 v[188:191], v183 offset:36896
	ds_read_b128 v[192:195], v183 offset:36928
	ds_read_b128 v[196:199], v183 offset:36960
	v_exp_f32_e32 v92, v92
	v_exp_f32_e32 v93, v93
	v_add_f32_e32 v222, v222, v92
	v_add_f32_e32 v223, v223, v93
	v_cvt_pk_bf16_f32 v91, v92, v93
	v_mfma_f32_32x32x16_bf16 v[34:49], v[204:207], v[66:69], v[34:49]
	v_exp_f32_e32 v94, v94
	v_exp_f32_e32 v95, v95
	v_add_f32_e32 v179, v179, v94
	v_add_f32_e32 v221, v221, v95
	v_cvt_pk_bf16_f32 v92, v94, v95
	v_mfma_f32_32x32x16_bf16 v[18:33], v[200:203], v[82:85], v[18:33]
	v_exp_f32_e32 v96, v96
	v_exp_f32_e32 v97, v97
	v_add_f32_e32 v222, v222, v96
	v_add_f32_e32 v223, v223, v97
	v_cvt_pk_bf16_f32 v93, v96, v97
	v_mfma_f32_32x32x16_bf16 v[2:17], v[204:207], v[82:85], v[2:17]
	v_exp_f32_e32 v98, v98
	v_exp_f32_e32 v99, v99
	v_add_f32_e32 v178, v178, v98
	v_add_f32_e32 v218, v218, v99
	v_cvt_pk_bf16_f32 v98, v98, v99
	s_waitcnt lgkmcnt(4)
	v_mfma_f32_32x32x16_bf16 v[50:65], v[208:211], v[74:77], v[50:65]
	ds_read_b64_tr_b16 v[200:201], v216 offset:32256
	ds_read_b64_tr_b16 v[202:203], v216 offset:32832
	ds_read_b64_tr_b16 v[204:205], v216 offset:32320
	ds_read_b64_tr_b16 v[206:207], v216 offset:32896
	v_exp_f32_e32 v100, v100
	v_exp_f32_e32 v101, v101
	v_add_f32_e32 v219, v219, v100
	v_add_f32_e32 v220, v220, v101
	v_cvt_pk_bf16_f32 v99, v100, v101
	v_mfma_f32_32x32x16_bf16 v[34:49], v[212:215], v[74:77], v[34:49]
	v_exp_f32_e32 v102, v102
	v_exp_f32_e32 v103, v103
	v_add_f32_e32 v178, v178, v102
	v_add_f32_e32 v218, v218, v103
	v_cvt_pk_bf16_f32 v100, v102, v103
	v_mfma_f32_32x32x16_bf16 v[18:33], v[208:211], v[90:93], v[18:33]
	v_exp_f32_e32 v104, v104
	v_exp_f32_e32 v105, v105
	v_add_f32_e32 v219, v219, v104
	v_add_f32_e32 v220, v220, v105
	v_cvt_pk_bf16_f32 v101, v104, v105
	v_mfma_f32_32x32x16_bf16 v[2:17], v[212:215], v[90:93], v[2:17]
	v_exp_f32_e32 v114, v114
	v_exp_f32_e32 v115, v115
	v_add_f32_e32 v179, v179, v114
	v_add_f32_e32 v221, v221, v115
	v_cvt_pk_bf16_f32 v114, v114, v115
	s_waitcnt lgkmcnt(4)
	v_mfma_f32_32x32x16_bf16 v[66:81], v[184:187], v[130:133], 0
	ds_read_b64_tr_b16 v[208:209], v216 offset:34560
	ds_read_b64_tr_b16 v[210:211], v216 offset:35136
	ds_read_b64_tr_b16 v[212:213], v216 offset:34624
	ds_read_b64_tr_b16 v[214:215], v216 offset:35200
	v_exp_f32_e32 v116, v116
	v_exp_f32_e32 v117, v117
	v_add_f32_e32 v222, v222, v116
	v_add_f32_e32 v223, v223, v117
	v_cvt_pk_bf16_f32 v115, v116, v117
	v_mfma_f32_32x32x16_bf16 v[66:81], v[188:191], v[134:137], v[66:81]
	v_exp_f32_e32 v118, v118
	v_exp_f32_e32 v119, v119
	v_add_f32_e32 v179, v179, v118
	v_add_f32_e32 v221, v221, v119
	v_cvt_pk_bf16_f32 v116, v118, v119
	v_mfma_f32_32x32x16_bf16 v[66:81], v[192:195], v[146:149], v[66:81]
	v_exp_f32_e32 v120, v120
	v_exp_f32_e32 v121, v121
	v_add_f32_e32 v222, v222, v120
	v_add_f32_e32 v223, v223, v121
	v_cvt_pk_bf16_f32 v117, v120, v121
	v_mfma_f32_32x32x16_bf16 v[66:81], v[196:199], v[150:153], v[66:81]
	v_exp_f32_e32 v106, v106
	v_exp_f32_e32 v107, v107
	v_add_f32_e32 v178, v178, v106
	v_add_f32_e32 v218, v218, v107
	v_cvt_pk_bf16_f32 v106, v106, v107
	s_waitcnt lgkmcnt(4)
	v_mfma_f32_32x32x16_bf16 v[50:65], v[200:203], v[98:101], v[50:65]
	v_exp_f32_e32 v108, v108
	v_exp_f32_e32 v109, v109
	v_add_f32_e32 v219, v219, v108
	v_add_f32_e32 v220, v220, v109
	v_cvt_pk_bf16_f32 v107, v108, v109
	v_mfma_f32_32x32x16_bf16 v[34:49], v[204:207], v[98:101], v[34:49]
	v_exp_f32_e32 v110, v110
	v_exp_f32_e32 v111, v111
	v_add_f32_e32 v178, v178, v110
	v_add_f32_e32 v218, v218, v111
	v_cvt_pk_bf16_f32 v108, v110, v111
	v_mfma_f32_32x32x16_bf16 v[18:33], v[200:203], v[114:117], v[18:33]
	s_waitcnt vmcnt(0)
	ds_write_b128 v228, v[162:165] offset:18432
	ds_write_b128 v228, v[166:169] offset:27648
	v_exp_f32_e32 v112, v112
	v_exp_f32_e32 v113, v113
	v_add_f32_e32 v219, v219, v112
	v_add_f32_e32 v220, v220, v113
	v_cvt_pk_bf16_f32 v109, v112, v113
	v_mfma_f32_32x32x16_bf16 v[2:17], v[204:207], v[114:117], v[2:17]
	v_exp_f32_e32 v122, v122
	v_exp_f32_e32 v123, v123
	v_add_f32_e32 v179, v179, v122
	v_add_f32_e32 v221, v221, v123
	v_cvt_pk_bf16_f32 v122, v122, v123
	v_mfma_f32_32x32x16_bf16 v[82:97], v[184:187], v[154:157], 0
	v_exp_f32_e32 v124, v124
	v_exp_f32_e32 v125, v125
	v_add_f32_e32 v222, v222, v124
	v_add_f32_e32 v223, v223, v125
	v_cvt_pk_bf16_f32 v123, v124, v125
	v_mfma_f32_32x32x16_bf16 v[82:97], v[188:191], v[138:141], v[82:97]
	v_exp_f32_e32 v126, v126
	v_exp_f32_e32 v127, v127
	v_add_f32_e32 v179, v179, v126
	v_add_f32_e32 v221, v221, v127
	v_cvt_pk_bf16_f32 v124, v126, v127
	v_mfma_f32_32x32x16_bf16 v[82:97], v[192:195], v[142:145], v[82:97]
	v_exp_f32_e32 v128, v128
	v_exp_f32_e32 v129, v129
	v_add_f32_e32 v222, v222, v128
	v_add_f32_e32 v223, v223, v129
	v_cvt_pk_bf16_f32 v125, v128, v129
	v_mfma_f32_32x32x16_bf16 v[82:97], v[196:199], v[158:161], v[82:97]
	s_waitcnt lgkmcnt(0)
	s_barrier
	global_load_dwordx4 v[162:165], v[176:177], off
	global_load_dwordx4 v[166:169], v[176:177], off offset:256
	ds_read_b128 v[184:187], v183 offset:41472
	ds_read_b128 v[188:191], v183 offset:41504
	ds_read_b128 v[192:195], v183 offset:41536
	ds_read_b128 v[196:199], v183 offset:41568
	v_exp_f32_e32 v66, v66
	v_exp_f32_e32 v67, v67
	v_add_f32_e32 v178, v178, v66
	v_add_f32_e32 v218, v218, v67
	v_cvt_pk_bf16_f32 v66, v66, v67
	v_mfma_f32_32x32x16_bf16 v[50:65], v[208:211], v[106:109], v[50:65]
	v_exp_f32_e32 v68, v68
	v_exp_f32_e32 v69, v69
	v_add_f32_e32 v219, v219, v68
	v_add_f32_e32 v220, v220, v69
	v_cvt_pk_bf16_f32 v67, v68, v69
	v_mfma_f32_32x32x16_bf16 v[34:49], v[212:215], v[106:109], v[34:49]
	v_lshl_add_u64 v[176:177], v[176:177], 0, s[8:9]
	v_exp_f32_e32 v70, v70
	v_exp_f32_e32 v71, v71
	v_add_f32_e32 v178, v178, v70
	v_add_f32_e32 v218, v218, v71
	v_cvt_pk_bf16_f32 v68, v70, v71
	v_mfma_f32_32x32x16_bf16 v[18:33], v[208:211], v[122:125], v[18:33]
	v_exp_f32_e32 v72, v72
	v_exp_f32_e32 v73, v73
	v_add_f32_e32 v219, v219, v72
	v_add_f32_e32 v220, v220, v73
	v_cvt_pk_bf16_f32 v69, v72, v73
	v_mfma_f32_32x32x16_bf16 v[2:17], v[212:215], v[122:125], v[2:17]
	v_exp_f32_e32 v82, v82
	v_exp_f32_e32 v83, v83
	v_add_f32_e32 v179, v179, v82
	v_add_f32_e32 v221, v221, v83
	v_cvt_pk_bf16_f32 v82, v82, v83
	s_waitcnt lgkmcnt(0)
	v_mfma_f32_32x32x16_bf16 v[98:113], v[184:187], v[130:133], 0
	ds_read_b64_tr_b16 v[200:201], v216 offset:46080
	ds_read_b64_tr_b16 v[202:203], v216 offset:46656
	ds_read_b64_tr_b16 v[204:205], v216 offset:46144
	ds_read_b64_tr_b16 v[206:207], v216 offset:46720
	v_exp_f32_e32 v84, v84
	v_exp_f32_e32 v85, v85
	v_add_f32_e32 v222, v222, v84
	v_add_f32_e32 v223, v223, v85
	v_cvt_pk_bf16_f32 v83, v84, v85
	v_mfma_f32_32x32x16_bf16 v[98:113], v[188:191], v[134:137], v[98:113]
	ds_read_b64_tr_b16 v[208:209], v216 offset:48384
	ds_read_b64_tr_b16 v[210:211], v216 offset:48960
	ds_read_b64_tr_b16 v[212:213], v216 offset:48448
	ds_read_b64_tr_b16 v[214:215], v216 offset:49024
	v_exp_f32_e32 v86, v86
	v_exp_f32_e32 v87, v87
	v_add_f32_e32 v179, v179, v86
	v_add_f32_e32 v221, v221, v87
	v_cvt_pk_bf16_f32 v84, v86, v87
	v_mfma_f32_32x32x16_bf16 v[98:113], v[192:195], v[146:149], v[98:113]
	v_exp_f32_e32 v88, v88
	v_exp_f32_e32 v89, v89
	v_add_f32_e32 v222, v222, v88
	v_add_f32_e32 v223, v223, v89
	v_cvt_pk_bf16_f32 v85, v88, v89
	v_mfma_f32_32x32x16_bf16 v[98:113], v[196:199], v[150:153], v[98:113]
	v_exp_f32_e32 v74, v74
	v_exp_f32_e32 v75, v75
	v_add_f32_e32 v178, v178, v74
	v_add_f32_e32 v218, v218, v75
	v_cvt_pk_bf16_f32 v74, v74, v75
	v_mfma_f32_32x32x16_bf16 v[114:129], v[184:187], v[154:157], 0
	v_exp_f32_e32 v76, v76
	v_exp_f32_e32 v77, v77
	v_add_f32_e32 v219, v219, v76
	v_add_f32_e32 v220, v220, v77
	v_cvt_pk_bf16_f32 v75, v76, v77
	v_mfma_f32_32x32x16_bf16 v[114:129], v[188:191], v[138:141], v[114:129]
	v_exp_f32_e32 v78, v78
	v_exp_f32_e32 v79, v79
	v_add_f32_e32 v178, v178, v78
	v_add_f32_e32 v218, v218, v79
	v_cvt_pk_bf16_f32 v76, v78, v79
	v_mfma_f32_32x32x16_bf16 v[114:129], v[192:195], v[142:145], v[114:129]
	v_exp_f32_e32 v80, v80
	v_exp_f32_e32 v81, v81
	v_add_f32_e32 v219, v219, v80
	v_add_f32_e32 v220, v220, v81
	v_cvt_pk_bf16_f32 v77, v80, v81
	v_mfma_f32_32x32x16_bf16 v[114:129], v[196:199], v[158:161], v[114:129]
	v_exp_f32_e32 v90, v90
	v_exp_f32_e32 v91, v91
	v_add_f32_e32 v179, v179, v90
	v_add_f32_e32 v221, v221, v91
	v_cvt_pk_bf16_f32 v90, v90, v91
	s_waitcnt lgkmcnt(4)
	v_mfma_f32_32x32x16_bf16 v[50:65], v[200:203], v[66:69], v[50:65]
	ds_read_b128 v[184:187], v226
	ds_read_b128 v[188:191], v226 offset:32
	ds_read_b128 v[192:195], v226 offset:64
	ds_read_b128 v[196:199], v226 offset:96
	v_exp_f32_e32 v92, v92
	v_exp_f32_e32 v93, v93
	v_add_f32_e32 v222, v222, v92
	v_add_f32_e32 v223, v223, v93
	v_cvt_pk_bf16_f32 v91, v92, v93
	v_mfma_f32_32x32x16_bf16 v[34:49], v[204:207], v[66:69], v[34:49]
	v_exp_f32_e32 v94, v94
	v_exp_f32_e32 v95, v95
	v_add_f32_e32 v179, v179, v94
	v_add_f32_e32 v221, v221, v95
	v_cvt_pk_bf16_f32 v92, v94, v95
	v_mfma_f32_32x32x16_bf16 v[18:33], v[200:203], v[82:85], v[18:33]
	v_exp_f32_e32 v96, v96
	v_exp_f32_e32 v97, v97
	v_add_f32_e32 v222, v222, v96
	v_add_f32_e32 v223, v223, v97
	v_cvt_pk_bf16_f32 v93, v96, v97
	v_mfma_f32_32x32x16_bf16 v[2:17], v[204:207], v[82:85], v[2:17]
	v_exp_f32_e32 v98, v98
	v_exp_f32_e32 v99, v99
	v_add_f32_e32 v178, v178, v98
	v_add_f32_e32 v218, v218, v99
	v_cvt_pk_bf16_f32 v98, v98, v99
	s_waitcnt lgkmcnt(4)
	v_mfma_f32_32x32x16_bf16 v[50:65], v[208:211], v[74:77], v[50:65]
	ds_read_b64_tr_b16 v[200:201], v216 offset:50688
	ds_read_b64_tr_b16 v[202:203], v216 offset:51264
	ds_read_b64_tr_b16 v[204:205], v216 offset:50752
	ds_read_b64_tr_b16 v[206:207], v216 offset:51328
	v_exp_f32_e32 v100, v100
	v_exp_f32_e32 v101, v101
	v_add_f32_e32 v219, v219, v100
	v_add_f32_e32 v220, v220, v101
	v_cvt_pk_bf16_f32 v99, v100, v101
	v_mfma_f32_32x32x16_bf16 v[34:49], v[212:215], v[74:77], v[34:49]
	v_exp_f32_e32 v102, v102
	v_exp_f32_e32 v103, v103
	v_add_f32_e32 v178, v178, v102
	v_add_f32_e32 v218, v218, v103
	v_cvt_pk_bf16_f32 v100, v102, v103
	v_mfma_f32_32x32x16_bf16 v[18:33], v[208:211], v[90:93], v[18:33]
	v_exp_f32_e32 v104, v104
	v_exp_f32_e32 v105, v105
	v_add_f32_e32 v219, v219, v104
	v_add_f32_e32 v220, v220, v105
	v_cvt_pk_bf16_f32 v101, v104, v105
	v_mfma_f32_32x32x16_bf16 v[2:17], v[212:215], v[90:93], v[2:17]
	v_exp_f32_e32 v114, v114
	v_exp_f32_e32 v115, v115
	v_add_f32_e32 v179, v179, v114
	v_add_f32_e32 v221, v221, v115
	v_cvt_pk_bf16_f32 v114, v114, v115
	s_waitcnt lgkmcnt(4)
	v_mfma_f32_32x32x16_bf16 v[66:81], v[184:187], v[130:133], 0
	ds_read_b64_tr_b16 v[208:209], v216 offset:52992
	ds_read_b64_tr_b16 v[210:211], v216 offset:53568
	ds_read_b64_tr_b16 v[212:213], v216 offset:53056
	ds_read_b64_tr_b16 v[214:215], v216 offset:53632
	v_exp_f32_e32 v116, v116
	v_exp_f32_e32 v117, v117
	v_add_f32_e32 v222, v222, v116
	v_add_f32_e32 v223, v223, v117
	v_cvt_pk_bf16_f32 v115, v116, v117
	v_mfma_f32_32x32x16_bf16 v[66:81], v[188:191], v[134:137], v[66:81]
	v_exp_f32_e32 v118, v118
	v_exp_f32_e32 v119, v119
	v_add_f32_e32 v179, v179, v118
	v_add_f32_e32 v221, v221, v119
	v_cvt_pk_bf16_f32 v116, v118, v119
	v_mfma_f32_32x32x16_bf16 v[66:81], v[192:195], v[146:149], v[66:81]
	v_exp_f32_e32 v120, v120
	v_exp_f32_e32 v121, v121
	v_add_f32_e32 v222, v222, v120
	v_add_f32_e32 v223, v223, v121
	v_cvt_pk_bf16_f32 v117, v120, v121
	v_mfma_f32_32x32x16_bf16 v[66:81], v[196:199], v[150:153], v[66:81]
	v_exp_f32_e32 v106, v106
	v_exp_f32_e32 v107, v107
	v_add_f32_e32 v178, v178, v106
	v_add_f32_e32 v218, v218, v107
	v_cvt_pk_bf16_f32 v106, v106, v107
	s_waitcnt lgkmcnt(4)
	v_mfma_f32_32x32x16_bf16 v[50:65], v[200:203], v[98:101], v[50:65]
	v_exp_f32_e32 v108, v108
	v_exp_f32_e32 v109, v109
	v_add_f32_e32 v219, v219, v108
	v_add_f32_e32 v220, v220, v109
	v_cvt_pk_bf16_f32 v107, v108, v109
	v_mfma_f32_32x32x16_bf16 v[34:49], v[204:207], v[98:101], v[34:49]
	v_exp_f32_e32 v110, v110
	v_exp_f32_e32 v111, v111
	v_add_f32_e32 v178, v178, v110
	v_add_f32_e32 v218, v218, v111
	v_cvt_pk_bf16_f32 v108, v110, v111
	v_mfma_f32_32x32x16_bf16 v[18:33], v[200:203], v[114:117], v[18:33]
	s_waitcnt vmcnt(0)
	ds_write_b128 v228, v[162:165] offset:36864
	ds_write_b128 v228, v[166:169] offset:46080
	v_exp_f32_e32 v112, v112
	v_exp_f32_e32 v113, v113
	v_add_f32_e32 v219, v219, v112
	v_add_f32_e32 v220, v220, v113
	v_cvt_pk_bf16_f32 v109, v112, v113
	v_mfma_f32_32x32x16_bf16 v[2:17], v[204:207], v[114:117], v[2:17]
	v_exp_f32_e32 v122, v122
	v_exp_f32_e32 v123, v123
	v_add_f32_e32 v179, v179, v122
	v_add_f32_e32 v221, v221, v123
	v_cvt_pk_bf16_f32 v122, v122, v123
	v_mfma_f32_32x32x16_bf16 v[82:97], v[184:187], v[154:157], 0
	v_exp_f32_e32 v124, v124
	v_exp_f32_e32 v125, v125
	v_add_f32_e32 v222, v222, v124
	v_add_f32_e32 v223, v223, v125
	v_cvt_pk_bf16_f32 v123, v124, v125
	v_mfma_f32_32x32x16_bf16 v[82:97], v[188:191], v[138:141], v[82:97]
	v_exp_f32_e32 v126, v126
	v_exp_f32_e32 v127, v127
	v_add_f32_e32 v179, v179, v126
	v_add_f32_e32 v221, v221, v127
	v_cvt_pk_bf16_f32 v124, v126, v127
	v_mfma_f32_32x32x16_bf16 v[82:97], v[192:195], v[142:145], v[82:97]
	v_exp_f32_e32 v128, v128
	v_exp_f32_e32 v129, v129
	v_add_f32_e32 v222, v222, v128
	v_add_f32_e32 v223, v223, v129
	v_cvt_pk_bf16_f32 v125, v128, v129
	v_mfma_f32_32x32x16_bf16 v[82:97], v[196:199], v[158:161], v[82:97]
	global_load_dwordx4 v[162:165], v[176:177], off
	global_load_dwordx4 v[166:169], v[176:177], off offset:256
	ds_read_b128 v[184:187], v226 offset:4608
	ds_read_b128 v[188:191], v226 offset:4640
	ds_read_b128 v[192:195], v226 offset:4672
	ds_read_b128 v[196:199], v226 offset:4704
	v_exp_f32_e32 v66, v66
	v_exp_f32_e32 v67, v67
	v_add_f32_e32 v178, v178, v66
	v_add_f32_e32 v218, v218, v67
	v_cvt_pk_bf16_f32 v66, v66, v67
	s_waitcnt lgkmcnt(6)
	v_mfma_f32_32x32x16_bf16 v[50:65], v[208:211], v[106:109], v[50:65]
	v_exp_f32_e32 v68, v68
	v_exp_f32_e32 v69, v69
	v_add_f32_e32 v219, v219, v68
	v_add_f32_e32 v220, v220, v69
	v_cvt_pk_bf16_f32 v67, v68, v69
	v_mfma_f32_32x32x16_bf16 v[34:49], v[212:215], v[106:109], v[34:49]
	v_lshl_add_u64 v[176:177], v[176:177], 0, s[8:9]
	v_exp_f32_e32 v70, v70
	v_exp_f32_e32 v71, v71
	v_add_f32_e32 v178, v178, v70
	v_add_f32_e32 v218, v218, v71
	v_cvt_pk_bf16_f32 v68, v70, v71
	v_mfma_f32_32x32x16_bf16 v[18:33], v[208:211], v[122:125], v[18:33]
	v_exp_f32_e32 v72, v72
	v_exp_f32_e32 v73, v73
	v_add_f32_e32 v219, v219, v72
	v_add_f32_e32 v220, v220, v73
	v_cvt_pk_bf16_f32 v69, v72, v73
	v_mfma_f32_32x32x16_bf16 v[2:17], v[212:215], v[122:125], v[2:17]
	v_exp_f32_e32 v82, v82
	v_exp_f32_e32 v83, v83
	v_add_f32_e32 v179, v179, v82
	v_add_f32_e32 v221, v221, v83
	v_cvt_pk_bf16_f32 v82, v82, v83
	s_waitcnt lgkmcnt(0)
	v_mfma_f32_32x32x16_bf16 v[98:113], v[184:187], v[130:133], 0
	ds_read_b64_tr_b16 v[200:201], v227 offset:9216
	ds_read_b64_tr_b16 v[202:203], v227 offset:9792
	ds_read_b64_tr_b16 v[204:205], v227 offset:9280
	ds_read_b64_tr_b16 v[206:207], v227 offset:9856
	v_exp_f32_e32 v84, v84
	v_exp_f32_e32 v85, v85
	v_add_f32_e32 v222, v222, v84
	v_add_f32_e32 v223, v223, v85
	v_cvt_pk_bf16_f32 v83, v84, v85
	v_mfma_f32_32x32x16_bf16 v[98:113], v[188:191], v[134:137], v[98:113]
	ds_read_b64_tr_b16 v[208:209], v227 offset:11520
	ds_read_b64_tr_b16 v[210:211], v227 offset:12096
	ds_read_b64_tr_b16 v[212:213], v227 offset:11584
	ds_read_b64_tr_b16 v[214:215], v227 offset:12160
	v_exp_f32_e32 v86, v86
	v_exp_f32_e32 v87, v87
	v_add_f32_e32 v179, v179, v86
	v_add_f32_e32 v221, v221, v87
	v_cvt_pk_bf16_f32 v84, v86, v87
	v_mfma_f32_32x32x16_bf16 v[98:113], v[192:195], v[146:149], v[98:113]
	v_exp_f32_e32 v88, v88
	v_exp_f32_e32 v89, v89
	v_add_f32_e32 v222, v222, v88
	v_add_f32_e32 v223, v223, v89
	v_cvt_pk_bf16_f32 v85, v88, v89
	v_mfma_f32_32x32x16_bf16 v[98:113], v[196:199], v[150:153], v[98:113]
	v_exp_f32_e32 v74, v74
	v_exp_f32_e32 v75, v75
	v_add_f32_e32 v178, v178, v74
	v_add_f32_e32 v218, v218, v75
	v_cvt_pk_bf16_f32 v74, v74, v75
	v_mfma_f32_32x32x16_bf16 v[114:129], v[184:187], v[154:157], 0
	v_exp_f32_e32 v76, v76
	v_exp_f32_e32 v77, v77
	v_add_f32_e32 v219, v219, v76
	v_add_f32_e32 v220, v220, v77
	v_cvt_pk_bf16_f32 v75, v76, v77
	v_mfma_f32_32x32x16_bf16 v[114:129], v[188:191], v[138:141], v[114:129]
	v_exp_f32_e32 v78, v78
	v_exp_f32_e32 v79, v79
	v_add_f32_e32 v178, v178, v78
	v_add_f32_e32 v218, v218, v79
	v_cvt_pk_bf16_f32 v76, v78, v79
	v_mfma_f32_32x32x16_bf16 v[114:129], v[192:195], v[142:145], v[114:129]
	v_exp_f32_e32 v80, v80
	v_exp_f32_e32 v81, v81
	v_add_f32_e32 v219, v219, v80
	v_add_f32_e32 v220, v220, v81
	v_cvt_pk_bf16_f32 v77, v80, v81
	v_mfma_f32_32x32x16_bf16 v[114:129], v[196:199], v[158:161], v[114:129]
	v_exp_f32_e32 v90, v90
	v_exp_f32_e32 v91, v91
	v_add_f32_e32 v179, v179, v90
	v_add_f32_e32 v221, v221, v91
	v_cvt_pk_bf16_f32 v90, v90, v91
	s_waitcnt lgkmcnt(4)
	v_mfma_f32_32x32x16_bf16 v[50:65], v[200:203], v[66:69], v[50:65]
	ds_read_b128 v[184:187], v226 offset:18432
	ds_read_b128 v[188:191], v226 offset:18464
	ds_read_b128 v[192:195], v226 offset:18496
	ds_read_b128 v[196:199], v226 offset:18528
	v_exp_f32_e32 v92, v92
	v_exp_f32_e32 v93, v93
	v_add_f32_e32 v222, v222, v92
	v_add_f32_e32 v223, v223, v93
	v_cvt_pk_bf16_f32 v91, v92, v93
	v_mfma_f32_32x32x16_bf16 v[34:49], v[204:207], v[66:69], v[34:49]
	v_exp_f32_e32 v94, v94
	v_exp_f32_e32 v95, v95
	v_add_f32_e32 v179, v179, v94
	v_add_f32_e32 v221, v221, v95
	v_cvt_pk_bf16_f32 v92, v94, v95
	v_mfma_f32_32x32x16_bf16 v[18:33], v[200:203], v[82:85], v[18:33]
	v_exp_f32_e32 v96, v96
	v_exp_f32_e32 v97, v97
	v_add_f32_e32 v222, v222, v96
	v_add_f32_e32 v223, v223, v97
	v_cvt_pk_bf16_f32 v93, v96, v97
	v_mfma_f32_32x32x16_bf16 v[2:17], v[204:207], v[82:85], v[2:17]
	v_exp_f32_e32 v98, v98
	v_exp_f32_e32 v99, v99
	v_add_f32_e32 v178, v178, v98
	v_add_f32_e32 v218, v218, v99
	v_cvt_pk_bf16_f32 v98, v98, v99
	s_waitcnt lgkmcnt(4)
	v_mfma_f32_32x32x16_bf16 v[50:65], v[208:211], v[74:77], v[50:65]
	ds_read_b64_tr_b16 v[200:201], v227 offset:13824
	ds_read_b64_tr_b16 v[202:203], v227 offset:14400
	ds_read_b64_tr_b16 v[204:205], v227 offset:13888
	ds_read_b64_tr_b16 v[206:207], v227 offset:14464
	v_exp_f32_e32 v100, v100
	v_exp_f32_e32 v101, v101
	v_add_f32_e32 v219, v219, v100
	v_add_f32_e32 v220, v220, v101
	v_cvt_pk_bf16_f32 v99, v100, v101
	v_mfma_f32_32x32x16_bf16 v[34:49], v[212:215], v[74:77], v[34:49]
	v_exp_f32_e32 v102, v102
	v_exp_f32_e32 v103, v103
	v_add_f32_e32 v178, v178, v102
	v_add_f32_e32 v218, v218, v103
	v_cvt_pk_bf16_f32 v100, v102, v103
	v_mfma_f32_32x32x16_bf16 v[18:33], v[208:211], v[90:93], v[18:33]
	v_exp_f32_e32 v104, v104
	v_exp_f32_e32 v105, v105
	v_add_f32_e32 v219, v219, v104
	v_add_f32_e32 v220, v220, v105
	v_cvt_pk_bf16_f32 v101, v104, v105
	v_mfma_f32_32x32x16_bf16 v[2:17], v[212:215], v[90:93], v[2:17]
	v_exp_f32_e32 v114, v114
	v_exp_f32_e32 v115, v115
	v_add_f32_e32 v179, v179, v114
	v_add_f32_e32 v221, v221, v115
	v_cvt_pk_bf16_f32 v114, v114, v115
	s_waitcnt lgkmcnt(4)
	v_mfma_f32_32x32x16_bf16 v[66:81], v[184:187], v[130:133], 0
	ds_read_b64_tr_b16 v[208:209], v227 offset:16128
	ds_read_b64_tr_b16 v[210:211], v227 offset:16704
	ds_read_b64_tr_b16 v[212:213], v227 offset:16192
	ds_read_b64_tr_b16 v[214:215], v227 offset:16768
	v_exp_f32_e32 v116, v116
	v_exp_f32_e32 v117, v117
	v_add_f32_e32 v222, v222, v116
	v_add_f32_e32 v223, v223, v117
	v_cvt_pk_bf16_f32 v115, v116, v117
	v_mfma_f32_32x32x16_bf16 v[66:81], v[188:191], v[134:137], v[66:81]
	v_exp_f32_e32 v118, v118
	v_exp_f32_e32 v119, v119
	v_add_f32_e32 v179, v179, v118
	v_add_f32_e32 v221, v221, v119
	v_cvt_pk_bf16_f32 v116, v118, v119
	v_mfma_f32_32x32x16_bf16 v[66:81], v[192:195], v[146:149], v[66:81]
	v_exp_f32_e32 v120, v120
	v_exp_f32_e32 v121, v121
	v_add_f32_e32 v222, v222, v120
	v_add_f32_e32 v223, v223, v121
	v_cvt_pk_bf16_f32 v117, v120, v121
	v_mfma_f32_32x32x16_bf16 v[66:81], v[196:199], v[150:153], v[66:81]
	v_exp_f32_e32 v106, v106
	v_exp_f32_e32 v107, v107
	v_add_f32_e32 v178, v178, v106
	v_add_f32_e32 v218, v218, v107
	v_cvt_pk_bf16_f32 v106, v106, v107
	s_waitcnt lgkmcnt(4)
	v_mfma_f32_32x32x16_bf16 v[50:65], v[200:203], v[98:101], v[50:65]
	v_exp_f32_e32 v108, v108
	v_exp_f32_e32 v109, v109
	v_add_f32_e32 v219, v219, v108
	v_add_f32_e32 v220, v220, v109
	v_cvt_pk_bf16_f32 v107, v108, v109
	v_mfma_f32_32x32x16_bf16 v[34:49], v[204:207], v[98:101], v[34:49]
	v_exp_f32_e32 v110, v110
	v_exp_f32_e32 v111, v111
	v_add_f32_e32 v178, v178, v110
	v_add_f32_e32 v218, v218, v111
	v_cvt_pk_bf16_f32 v108, v110, v111
	v_mfma_f32_32x32x16_bf16 v[18:33], v[200:203], v[114:117], v[18:33]
	s_waitcnt vmcnt(0)
	ds_write_b128 v180, v[162:165]
	ds_write_b128 v180, v[166:169] offset:9216
	v_exp_f32_e32 v112, v112
	v_exp_f32_e32 v113, v113
	v_add_f32_e32 v219, v219, v112
	v_add_f32_e32 v220, v220, v113
	v_cvt_pk_bf16_f32 v109, v112, v113
	v_mfma_f32_32x32x16_bf16 v[2:17], v[204:207], v[114:117], v[2:17]
	v_exp_f32_e32 v122, v122
	v_exp_f32_e32 v123, v123
	v_add_f32_e32 v179, v179, v122
	v_add_f32_e32 v221, v221, v123
	v_cvt_pk_bf16_f32 v122, v122, v123
	v_mfma_f32_32x32x16_bf16 v[82:97], v[184:187], v[154:157], 0
	v_exp_f32_e32 v124, v124
	v_exp_f32_e32 v125, v125
	v_add_f32_e32 v222, v222, v124
	v_add_f32_e32 v223, v223, v125
	v_cvt_pk_bf16_f32 v123, v124, v125
	v_mfma_f32_32x32x16_bf16 v[82:97], v[188:191], v[138:141], v[82:97]
	v_exp_f32_e32 v126, v126
	v_exp_f32_e32 v127, v127
	v_add_f32_e32 v179, v179, v126
	v_add_f32_e32 v221, v221, v127
	v_cvt_pk_bf16_f32 v124, v126, v127
	v_mfma_f32_32x32x16_bf16 v[82:97], v[192:195], v[142:145], v[82:97]
	v_exp_f32_e32 v128, v128
	v_exp_f32_e32 v129, v129
	v_add_f32_e32 v222, v222, v128
	v_add_f32_e32 v223, v223, v129
	v_cvt_pk_bf16_f32 v125, v128, v129
	v_mfma_f32_32x32x16_bf16 v[82:97], v[196:199], v[158:161], v[82:97]
	s_waitcnt lgkmcnt(0)
	s_barrier
	global_load_dwordx4 v[162:165], v[176:177], off
	global_load_dwordx4 v[166:169], v[176:177], off offset:256
	ds_read_b128 v[184:187], v226 offset:23040
	ds_read_b128 v[188:191], v226 offset:23072
	ds_read_b128 v[192:195], v226 offset:23104
	ds_read_b128 v[196:199], v226 offset:23136
	v_exp_f32_e32 v66, v66
	v_exp_f32_e32 v67, v67
	v_add_f32_e32 v178, v178, v66
	v_add_f32_e32 v218, v218, v67
	v_cvt_pk_bf16_f32 v66, v66, v67
	v_mfma_f32_32x32x16_bf16 v[50:65], v[208:211], v[106:109], v[50:65]
	v_exp_f32_e32 v68, v68
	v_exp_f32_e32 v69, v69
	v_add_f32_e32 v219, v219, v68
	v_add_f32_e32 v220, v220, v69
	v_cvt_pk_bf16_f32 v67, v68, v69
	v_mfma_f32_32x32x16_bf16 v[34:49], v[212:215], v[106:109], v[34:49]
	v_lshl_add_u64 v[176:177], v[176:177], 0, s[8:9]
	v_exp_f32_e32 v70, v70
	v_exp_f32_e32 v71, v71
	v_add_f32_e32 v178, v178, v70
	v_add_f32_e32 v218, v218, v71
	v_cvt_pk_bf16_f32 v68, v70, v71
	v_mfma_f32_32x32x16_bf16 v[18:33], v[208:211], v[122:125], v[18:33]
	v_exp_f32_e32 v72, v72
	v_exp_f32_e32 v73, v73
	v_add_f32_e32 v219, v219, v72
	v_add_f32_e32 v220, v220, v73
	v_cvt_pk_bf16_f32 v69, v72, v73
	v_mfma_f32_32x32x16_bf16 v[2:17], v[212:215], v[122:125], v[2:17]
	v_exp_f32_e32 v82, v82
	v_exp_f32_e32 v83, v83
	v_add_f32_e32 v179, v179, v82
	v_add_f32_e32 v221, v221, v83
	v_cvt_pk_bf16_f32 v82, v82, v83
	s_waitcnt lgkmcnt(0)
	v_mfma_f32_32x32x16_bf16 v[98:113], v[184:187], v[130:133], 0
	ds_read_b64_tr_b16 v[200:201], v227 offset:27648
	ds_read_b64_tr_b16 v[202:203], v227 offset:28224
	ds_read_b64_tr_b16 v[204:205], v227 offset:27712
	ds_read_b64_tr_b16 v[206:207], v227 offset:28288
	v_exp_f32_e32 v84, v84
	v_exp_f32_e32 v85, v85
	v_add_f32_e32 v222, v222, v84
	v_add_f32_e32 v223, v223, v85
	v_cvt_pk_bf16_f32 v83, v84, v85
	v_mfma_f32_32x32x16_bf16 v[98:113], v[188:191], v[134:137], v[98:113]
	ds_read_b64_tr_b16 v[208:209], v227 offset:29952
	ds_read_b64_tr_b16 v[210:211], v227 offset:30528
	ds_read_b64_tr_b16 v[212:213], v227 offset:30016
	ds_read_b64_tr_b16 v[214:215], v227 offset:30592
	v_exp_f32_e32 v86, v86
	v_exp_f32_e32 v87, v87
	v_add_f32_e32 v179, v179, v86
	v_add_f32_e32 v221, v221, v87
	v_cvt_pk_bf16_f32 v84, v86, v87
	v_mfma_f32_32x32x16_bf16 v[98:113], v[192:195], v[146:149], v[98:113]
	v_exp_f32_e32 v88, v88
	v_exp_f32_e32 v89, v89
	v_add_f32_e32 v222, v222, v88
	v_add_f32_e32 v223, v223, v89
	v_cvt_pk_bf16_f32 v85, v88, v89
	v_mfma_f32_32x32x16_bf16 v[98:113], v[196:199], v[150:153], v[98:113]
	v_exp_f32_e32 v74, v74
	v_exp_f32_e32 v75, v75
	v_add_f32_e32 v178, v178, v74
	v_add_f32_e32 v218, v218, v75
	v_cvt_pk_bf16_f32 v74, v74, v75
	v_mfma_f32_32x32x16_bf16 v[114:129], v[184:187], v[154:157], 0
	v_exp_f32_e32 v76, v76
	v_exp_f32_e32 v77, v77
	v_add_f32_e32 v219, v219, v76
	v_add_f32_e32 v220, v220, v77
	v_cvt_pk_bf16_f32 v75, v76, v77
	v_mfma_f32_32x32x16_bf16 v[114:129], v[188:191], v[138:141], v[114:129]
	v_exp_f32_e32 v78, v78
	v_exp_f32_e32 v79, v79
	v_add_f32_e32 v178, v178, v78
	v_add_f32_e32 v218, v218, v79
	v_cvt_pk_bf16_f32 v76, v78, v79
	v_mfma_f32_32x32x16_bf16 v[114:129], v[192:195], v[142:145], v[114:129]
	v_exp_f32_e32 v80, v80
	v_exp_f32_e32 v81, v81
	v_add_f32_e32 v219, v219, v80
	v_add_f32_e32 v220, v220, v81
	v_cvt_pk_bf16_f32 v77, v80, v81
	v_mfma_f32_32x32x16_bf16 v[114:129], v[196:199], v[158:161], v[114:129]
	v_exp_f32_e32 v90, v90
	v_exp_f32_e32 v91, v91
	v_add_f32_e32 v179, v179, v90
	v_add_f32_e32 v221, v221, v91
	v_cvt_pk_bf16_f32 v90, v90, v91
	s_waitcnt lgkmcnt(4)
	v_mfma_f32_32x32x16_bf16 v[50:65], v[200:203], v[66:69], v[50:65]
	ds_read_b128 v[184:187], v226 offset:36864
	ds_read_b128 v[188:191], v226 offset:36896
	ds_read_b128 v[192:195], v226 offset:36928
	ds_read_b128 v[196:199], v226 offset:36960
	v_exp_f32_e32 v92, v92
	v_exp_f32_e32 v93, v93
	v_add_f32_e32 v222, v222, v92
	v_add_f32_e32 v223, v223, v93
	v_cvt_pk_bf16_f32 v91, v92, v93
	v_mfma_f32_32x32x16_bf16 v[34:49], v[204:207], v[66:69], v[34:49]
	v_exp_f32_e32 v94, v94
	v_exp_f32_e32 v95, v95
	v_add_f32_e32 v179, v179, v94
	v_add_f32_e32 v221, v221, v95
	v_cvt_pk_bf16_f32 v92, v94, v95
	v_mfma_f32_32x32x16_bf16 v[18:33], v[200:203], v[82:85], v[18:33]
	v_exp_f32_e32 v96, v96
	v_exp_f32_e32 v97, v97
	v_add_f32_e32 v222, v222, v96
	v_add_f32_e32 v223, v223, v97
	v_cvt_pk_bf16_f32 v93, v96, v97
	v_mfma_f32_32x32x16_bf16 v[2:17], v[204:207], v[82:85], v[2:17]
	v_exp_f32_e32 v98, v98
	v_exp_f32_e32 v99, v99
	v_add_f32_e32 v178, v178, v98
	v_add_f32_e32 v218, v218, v99
	v_cvt_pk_bf16_f32 v98, v98, v99
	s_waitcnt lgkmcnt(4)
	v_mfma_f32_32x32x16_bf16 v[50:65], v[208:211], v[74:77], v[50:65]
	ds_read_b64_tr_b16 v[200:201], v227 offset:32256
	ds_read_b64_tr_b16 v[202:203], v227 offset:32832
	ds_read_b64_tr_b16 v[204:205], v227 offset:32320
	ds_read_b64_tr_b16 v[206:207], v227 offset:32896
	v_exp_f32_e32 v100, v100
	v_exp_f32_e32 v101, v101
	v_add_f32_e32 v219, v219, v100
	v_add_f32_e32 v220, v220, v101
	v_cvt_pk_bf16_f32 v99, v100, v101
	v_mfma_f32_32x32x16_bf16 v[34:49], v[212:215], v[74:77], v[34:49]
	v_exp_f32_e32 v102, v102
	v_exp_f32_e32 v103, v103
	v_add_f32_e32 v178, v178, v102
	v_add_f32_e32 v218, v218, v103
	v_cvt_pk_bf16_f32 v100, v102, v103
	v_mfma_f32_32x32x16_bf16 v[18:33], v[208:211], v[90:93], v[18:33]
	v_exp_f32_e32 v104, v104
	v_exp_f32_e32 v105, v105
	v_add_f32_e32 v219, v219, v104
	v_add_f32_e32 v220, v220, v105
	v_cvt_pk_bf16_f32 v101, v104, v105
	v_mfma_f32_32x32x16_bf16 v[2:17], v[212:215], v[90:93], v[2:17]
	v_exp_f32_e32 v114, v114
	v_exp_f32_e32 v115, v115
	v_add_f32_e32 v179, v179, v114
	v_add_f32_e32 v221, v221, v115
	v_cvt_pk_bf16_f32 v114, v114, v115
	s_waitcnt lgkmcnt(4)
	v_mfma_f32_32x32x16_bf16 v[66:81], v[184:187], v[130:133], 0
	ds_read_b64_tr_b16 v[208:209], v227 offset:34560
	ds_read_b64_tr_b16 v[210:211], v227 offset:35136
	ds_read_b64_tr_b16 v[212:213], v227 offset:34624
	ds_read_b64_tr_b16 v[214:215], v227 offset:35200
	v_exp_f32_e32 v116, v116
	v_exp_f32_e32 v117, v117
	v_add_f32_e32 v222, v222, v116
	v_add_f32_e32 v223, v223, v117
	v_cvt_pk_bf16_f32 v115, v116, v117
	v_mfma_f32_32x32x16_bf16 v[66:81], v[188:191], v[134:137], v[66:81]
	v_exp_f32_e32 v118, v118
	v_exp_f32_e32 v119, v119
	v_add_f32_e32 v179, v179, v118
	v_add_f32_e32 v221, v221, v119
	v_cvt_pk_bf16_f32 v116, v118, v119
	v_mfma_f32_32x32x16_bf16 v[66:81], v[192:195], v[146:149], v[66:81]
	v_exp_f32_e32 v120, v120
	v_exp_f32_e32 v121, v121
	v_add_f32_e32 v222, v222, v120
	v_add_f32_e32 v223, v223, v121
	v_cvt_pk_bf16_f32 v117, v120, v121
	v_mfma_f32_32x32x16_bf16 v[66:81], v[196:199], v[150:153], v[66:81]
	v_exp_f32_e32 v106, v106
	v_exp_f32_e32 v107, v107
	v_add_f32_e32 v178, v178, v106
	v_add_f32_e32 v218, v218, v107
	v_cvt_pk_bf16_f32 v106, v106, v107
	s_waitcnt lgkmcnt(4)
	v_mfma_f32_32x32x16_bf16 v[50:65], v[200:203], v[98:101], v[50:65]
	v_exp_f32_e32 v108, v108
	v_exp_f32_e32 v109, v109
	v_add_f32_e32 v219, v219, v108
	v_add_f32_e32 v220, v220, v109
	v_cvt_pk_bf16_f32 v107, v108, v109
	v_mfma_f32_32x32x16_bf16 v[34:49], v[204:207], v[98:101], v[34:49]
	v_exp_f32_e32 v110, v110
	v_exp_f32_e32 v111, v111
	v_add_f32_e32 v178, v178, v110
	v_add_f32_e32 v218, v218, v111
	v_cvt_pk_bf16_f32 v108, v110, v111
	v_mfma_f32_32x32x16_bf16 v[18:33], v[200:203], v[114:117], v[18:33]
	s_waitcnt vmcnt(0)
	ds_write_b128 v180, v[162:165] offset:18432
	ds_write_b128 v180, v[166:169] offset:27648
	v_exp_f32_e32 v112, v112
	v_exp_f32_e32 v113, v113
	v_add_f32_e32 v219, v219, v112
	v_add_f32_e32 v220, v220, v113
	v_cvt_pk_bf16_f32 v109, v112, v113
	v_mfma_f32_32x32x16_bf16 v[2:17], v[204:207], v[114:117], v[2:17]
	v_exp_f32_e32 v122, v122
	v_exp_f32_e32 v123, v123
	v_add_f32_e32 v179, v179, v122
	v_add_f32_e32 v221, v221, v123
	v_cvt_pk_bf16_f32 v122, v122, v123
	v_mfma_f32_32x32x16_bf16 v[82:97], v[184:187], v[154:157], 0
	v_exp_f32_e32 v124, v124
	v_exp_f32_e32 v125, v125
	v_add_f32_e32 v222, v222, v124
	v_add_f32_e32 v223, v223, v125
	v_cvt_pk_bf16_f32 v123, v124, v125
	v_mfma_f32_32x32x16_bf16 v[82:97], v[188:191], v[138:141], v[82:97]
	v_exp_f32_e32 v126, v126
	v_exp_f32_e32 v127, v127
	v_add_f32_e32 v179, v179, v126
	v_add_f32_e32 v221, v221, v127
	v_cvt_pk_bf16_f32 v124, v126, v127
	v_mfma_f32_32x32x16_bf16 v[82:97], v[192:195], v[142:145], v[82:97]
	v_exp_f32_e32 v128, v128
	v_exp_f32_e32 v129, v129
	v_add_f32_e32 v222, v222, v128
	v_add_f32_e32 v223, v223, v129
	v_cvt_pk_bf16_f32 v125, v128, v129
	v_mfma_f32_32x32x16_bf16 v[82:97], v[196:199], v[158:161], v[82:97]
	global_load_dwordx4 v[162:165], v[176:177], off
	global_load_dwordx4 v[166:169], v[176:177], off offset:256
	ds_read_b128 v[184:187], v226 offset:41472
	ds_read_b128 v[188:191], v226 offset:41504
	ds_read_b128 v[192:195], v226 offset:41536
	ds_read_b128 v[196:199], v226 offset:41568
	v_exp_f32_e32 v66, v66
	v_exp_f32_e32 v67, v67
	v_add_f32_e32 v178, v178, v66
	v_add_f32_e32 v218, v218, v67
	v_cvt_pk_bf16_f32 v66, v66, v67
	s_waitcnt lgkmcnt(6)
	v_mfma_f32_32x32x16_bf16 v[50:65], v[208:211], v[106:109], v[50:65]
	v_exp_f32_e32 v68, v68
	v_exp_f32_e32 v69, v69
	v_add_f32_e32 v219, v219, v68
	v_add_f32_e32 v220, v220, v69
	v_cvt_pk_bf16_f32 v67, v68, v69
	v_mfma_f32_32x32x16_bf16 v[34:49], v[212:215], v[106:109], v[34:49]
	v_lshl_add_u64 v[176:177], v[176:177], 0, s[8:9]
	v_exp_f32_e32 v70, v70
	v_exp_f32_e32 v71, v71
	v_add_f32_e32 v178, v178, v70
	v_add_f32_e32 v218, v218, v71
	v_cvt_pk_bf16_f32 v68, v70, v71
	v_mfma_f32_32x32x16_bf16 v[18:33], v[208:211], v[122:125], v[18:33]
	v_exp_f32_e32 v72, v72
	v_exp_f32_e32 v73, v73
	v_add_f32_e32 v219, v219, v72
	v_add_f32_e32 v220, v220, v73
	v_cvt_pk_bf16_f32 v69, v72, v73
	v_mfma_f32_32x32x16_bf16 v[2:17], v[212:215], v[122:125], v[2:17]
	v_exp_f32_e32 v82, v82
	v_exp_f32_e32 v83, v83
	v_add_f32_e32 v179, v179, v82
	v_add_f32_e32 v221, v221, v83
	v_cvt_pk_bf16_f32 v82, v82, v83
	s_waitcnt lgkmcnt(0)
	v_mfma_f32_32x32x16_bf16 v[98:113], v[184:187], v[130:133], 0
	ds_read_b64_tr_b16 v[200:201], v227 offset:46080
	ds_read_b64_tr_b16 v[202:203], v227 offset:46656
	ds_read_b64_tr_b16 v[204:205], v227 offset:46144
	ds_read_b64_tr_b16 v[206:207], v227 offset:46720
	v_exp_f32_e32 v84, v84
	v_exp_f32_e32 v85, v85
	v_add_f32_e32 v222, v222, v84
	v_add_f32_e32 v223, v223, v85
	v_cvt_pk_bf16_f32 v83, v84, v85
	v_mfma_f32_32x32x16_bf16 v[98:113], v[188:191], v[134:137], v[98:113]
	ds_read_b64_tr_b16 v[208:209], v227 offset:48384
	ds_read_b64_tr_b16 v[210:211], v227 offset:48960
	ds_read_b64_tr_b16 v[212:213], v227 offset:48448
	ds_read_b64_tr_b16 v[214:215], v227 offset:49024
	v_exp_f32_e32 v86, v86
	v_exp_f32_e32 v87, v87
	v_add_f32_e32 v179, v179, v86
	v_add_f32_e32 v221, v221, v87
	v_cvt_pk_bf16_f32 v84, v86, v87
	v_mfma_f32_32x32x16_bf16 v[98:113], v[192:195], v[146:149], v[98:113]
	v_exp_f32_e32 v88, v88
	v_exp_f32_e32 v89, v89
	v_add_f32_e32 v222, v222, v88
	v_add_f32_e32 v223, v223, v89
	v_cvt_pk_bf16_f32 v85, v88, v89
	v_mfma_f32_32x32x16_bf16 v[98:113], v[196:199], v[150:153], v[98:113]
	v_exp_f32_e32 v74, v74
	v_exp_f32_e32 v75, v75
	v_add_f32_e32 v178, v178, v74
	v_add_f32_e32 v218, v218, v75
	v_cvt_pk_bf16_f32 v74, v74, v75
	v_mfma_f32_32x32x16_bf16 v[114:129], v[184:187], v[154:157], 0
	v_exp_f32_e32 v76, v76
	v_exp_f32_e32 v77, v77
	v_add_f32_e32 v219, v219, v76
	v_add_f32_e32 v220, v220, v77
	v_cvt_pk_bf16_f32 v75, v76, v77
	v_mfma_f32_32x32x16_bf16 v[114:129], v[188:191], v[138:141], v[114:129]
	v_exp_f32_e32 v78, v78
	v_exp_f32_e32 v79, v79
	v_add_f32_e32 v178, v178, v78
	v_add_f32_e32 v218, v218, v79
	v_cvt_pk_bf16_f32 v76, v78, v79
	v_mfma_f32_32x32x16_bf16 v[114:129], v[192:195], v[142:145], v[114:129]
	v_exp_f32_e32 v80, v80
	v_exp_f32_e32 v81, v81
	v_add_f32_e32 v219, v219, v80
	v_add_f32_e32 v220, v220, v81
	v_cvt_pk_bf16_f32 v77, v80, v81
	v_mfma_f32_32x32x16_bf16 v[114:129], v[196:199], v[158:161], v[114:129]
	v_exp_f32_e32 v90, v90
	v_exp_f32_e32 v91, v91
	v_add_f32_e32 v179, v179, v90
	v_add_f32_e32 v221, v221, v91
	v_cvt_pk_bf16_f32 v90, v90, v91
	s_waitcnt lgkmcnt(4)
	v_mfma_f32_32x32x16_bf16 v[50:65], v[200:203], v[66:69], v[50:65]
	ds_read_b128 v[184:187], v183
	ds_read_b128 v[188:191], v183 offset:32
	ds_read_b128 v[192:195], v183 offset:64
	ds_read_b128 v[196:199], v183 offset:96
	v_exp_f32_e32 v92, v92
	v_exp_f32_e32 v93, v93
	v_add_f32_e32 v222, v222, v92
	v_add_f32_e32 v223, v223, v93
	v_cvt_pk_bf16_f32 v91, v92, v93
	v_mfma_f32_32x32x16_bf16 v[34:49], v[204:207], v[66:69], v[34:49]
	v_exp_f32_e32 v94, v94
	v_exp_f32_e32 v95, v95
	v_add_f32_e32 v179, v179, v94
	v_add_f32_e32 v221, v221, v95
	v_cvt_pk_bf16_f32 v92, v94, v95
	v_mfma_f32_32x32x16_bf16 v[18:33], v[200:203], v[82:85], v[18:33]
	v_exp_f32_e32 v96, v96
	v_exp_f32_e32 v97, v97
	v_add_f32_e32 v222, v222, v96
	v_add_f32_e32 v223, v223, v97
	v_cvt_pk_bf16_f32 v93, v96, v97
	v_mfma_f32_32x32x16_bf16 v[2:17], v[204:207], v[82:85], v[2:17]
	v_exp_f32_e32 v98, v98
	v_exp_f32_e32 v99, v99
	v_add_f32_e32 v178, v178, v98
	v_add_f32_e32 v218, v218, v99
	v_cvt_pk_bf16_f32 v98, v98, v99
	s_waitcnt lgkmcnt(4)
	v_mfma_f32_32x32x16_bf16 v[50:65], v[208:211], v[74:77], v[50:65]
	ds_read_b64_tr_b16 v[200:201], v227 offset:50688
	ds_read_b64_tr_b16 v[202:203], v227 offset:51264
	ds_read_b64_tr_b16 v[204:205], v227 offset:50752
	ds_read_b64_tr_b16 v[206:207], v227 offset:51328
	v_exp_f32_e32 v100, v100
	v_exp_f32_e32 v101, v101
	v_add_f32_e32 v219, v219, v100
	v_add_f32_e32 v220, v220, v101
	v_cvt_pk_bf16_f32 v99, v100, v101
	v_mfma_f32_32x32x16_bf16 v[34:49], v[212:215], v[74:77], v[34:49]
	v_exp_f32_e32 v102, v102
	v_exp_f32_e32 v103, v103
	v_add_f32_e32 v178, v178, v102
	v_add_f32_e32 v218, v218, v103
	v_cvt_pk_bf16_f32 v100, v102, v103
	v_mfma_f32_32x32x16_bf16 v[18:33], v[208:211], v[90:93], v[18:33]
	v_exp_f32_e32 v104, v104
	v_exp_f32_e32 v105, v105
	v_add_f32_e32 v219, v219, v104
	v_add_f32_e32 v220, v220, v105
	v_cvt_pk_bf16_f32 v101, v104, v105
	v_mfma_f32_32x32x16_bf16 v[2:17], v[212:215], v[90:93], v[2:17]
	v_exp_f32_e32 v114, v114
	v_exp_f32_e32 v115, v115
	v_add_f32_e32 v179, v179, v114
	v_add_f32_e32 v221, v221, v115
	v_cvt_pk_bf16_f32 v114, v114, v115
	s_waitcnt lgkmcnt(4)
	v_mfma_f32_32x32x16_bf16 v[66:81], v[184:187], v[130:133], 0
	ds_read_b64_tr_b16 v[208:209], v227 offset:52992
	ds_read_b64_tr_b16 v[210:211], v227 offset:53568
	ds_read_b64_tr_b16 v[212:213], v227 offset:53056
	ds_read_b64_tr_b16 v[214:215], v227 offset:53632
	v_exp_f32_e32 v116, v116
	v_exp_f32_e32 v117, v117
	v_add_f32_e32 v222, v222, v116
	v_add_f32_e32 v223, v223, v117
	v_cvt_pk_bf16_f32 v115, v116, v117
	v_mfma_f32_32x32x16_bf16 v[66:81], v[188:191], v[134:137], v[66:81]
	v_exp_f32_e32 v118, v118
	v_exp_f32_e32 v119, v119
	v_add_f32_e32 v179, v179, v118
	v_add_f32_e32 v221, v221, v119
	v_cvt_pk_bf16_f32 v116, v118, v119
	v_mfma_f32_32x32x16_bf16 v[66:81], v[192:195], v[146:149], v[66:81]
	v_exp_f32_e32 v120, v120
	v_exp_f32_e32 v121, v121
	v_add_f32_e32 v222, v222, v120
	v_add_f32_e32 v223, v223, v121
	v_cvt_pk_bf16_f32 v117, v120, v121
	v_mfma_f32_32x32x16_bf16 v[66:81], v[196:199], v[150:153], v[66:81]
	v_exp_f32_e32 v106, v106
	v_exp_f32_e32 v107, v107
	v_add_f32_e32 v178, v178, v106
	v_add_f32_e32 v218, v218, v107
	v_cvt_pk_bf16_f32 v106, v106, v107
	s_waitcnt lgkmcnt(4)
	v_mfma_f32_32x32x16_bf16 v[50:65], v[200:203], v[98:101], v[50:65]
	v_exp_f32_e32 v108, v108
	v_exp_f32_e32 v109, v109
	v_add_f32_e32 v219, v219, v108
	v_add_f32_e32 v220, v220, v109
	v_cvt_pk_bf16_f32 v107, v108, v109
	v_mfma_f32_32x32x16_bf16 v[34:49], v[204:207], v[98:101], v[34:49]
	v_exp_f32_e32 v110, v110
	v_exp_f32_e32 v111, v111
	v_add_f32_e32 v178, v178, v110
	v_add_f32_e32 v218, v218, v111
	v_cvt_pk_bf16_f32 v108, v110, v111
	v_mfma_f32_32x32x16_bf16 v[18:33], v[200:203], v[114:117], v[18:33]
	s_waitcnt vmcnt(0)
	ds_write_b128 v180, v[162:165] offset:36864
	ds_write_b128 v180, v[166:169] offset:46080
	v_exp_f32_e32 v112, v112
	v_exp_f32_e32 v113, v113
	v_add_f32_e32 v219, v219, v112
	v_add_f32_e32 v220, v220, v113
	v_cvt_pk_bf16_f32 v109, v112, v113
	v_mfma_f32_32x32x16_bf16 v[2:17], v[204:207], v[114:117], v[2:17]
	v_exp_f32_e32 v122, v122
	v_exp_f32_e32 v123, v123
	v_add_f32_e32 v179, v179, v122
	v_add_f32_e32 v221, v221, v123
	v_cvt_pk_bf16_f32 v122, v122, v123
	v_mfma_f32_32x32x16_bf16 v[82:97], v[184:187], v[154:157], 0
	v_exp_f32_e32 v124, v124
	v_exp_f32_e32 v125, v125
	v_add_f32_e32 v222, v222, v124
	v_add_f32_e32 v223, v223, v125
	v_cvt_pk_bf16_f32 v123, v124, v125
	v_mfma_f32_32x32x16_bf16 v[82:97], v[188:191], v[138:141], v[82:97]
	v_exp_f32_e32 v126, v126
	v_exp_f32_e32 v127, v127
	v_add_f32_e32 v179, v179, v126
	v_add_f32_e32 v221, v221, v127
	v_cvt_pk_bf16_f32 v124, v126, v127
	v_mfma_f32_32x32x16_bf16 v[82:97], v[192:195], v[142:145], v[82:97]
	v_exp_f32_e32 v128, v128
	v_exp_f32_e32 v129, v129
	v_add_f32_e32 v222, v222, v128
	v_add_f32_e32 v223, v223, v129
	v_cvt_pk_bf16_f32 v125, v128, v129
	v_mfma_f32_32x32x16_bf16 v[82:97], v[196:199], v[158:161], v[82:97]
	s_add_i32 s30, s30, 1
	s_cmpk_lt_u32 s30, 42
	s_cbranch_scc1 .Lat_loop
	s_waitcnt lgkmcnt(0)
	s_barrier
	global_load_dwordx4 v[162:165], v[176:177], off
	global_load_dwordx4 v[166:169], v[176:177], off offset:256
	ds_read_b128 v[184:187], v183 offset:4608
	ds_read_b128 v[188:191], v183 offset:4640
	ds_read_b128 v[192:195], v183 offset:4672
	ds_read_b128 v[196:199], v183 offset:4704
	v_exp_f32_e32 v66, v66
	v_exp_f32_e32 v67, v67
	v_add_f32_e32 v178, v178, v66
	v_add_f32_e32 v218, v218, v67
	v_cvt_pk_bf16_f32 v66, v66, v67
	v_mfma_f32_32x32x16_bf16 v[50:65], v[208:211], v[106:109], v[50:65]
	v_exp_f32_e32 v68, v68
	v_exp_f32_e32 v69, v69
	v_add_f32_e32 v219, v219, v68
	v_add_f32_e32 v220, v220, v69
	v_cvt_pk_bf16_f32 v67, v68, v69
	v_mfma_f32_32x32x16_bf16 v[34:49], v[212:215], v[106:109], v[34:49]
	v_lshl_add_u64 v[176:177], v[176:177], 0, s[8:9]
	v_exp_f32_e32 v70, v70
	v_exp_f32_e32 v71, v71
	v_add_f32_e32 v178, v178, v70
	v_add_f32_e32 v218, v218, v71
	v_cvt_pk_bf16_f32 v68, v70, v71
	v_mfma_f32_32x32x16_bf16 v[18:33], v[208:211], v[122:125], v[18:33]
	v_exp_f32_e32 v72, v72
	v_exp_f32_e32 v73, v73
	v_add_f32_e32 v219, v219, v72
	v_add_f32_e32 v220, v220, v73
	v_cvt_pk_bf16_f32 v69, v72, v73
	v_mfma_f32_32x32x16_bf16 v[2:17], v[212:215], v[122:125], v[2:17]
	v_exp_f32_e32 v82, v82
	v_exp_f32_e32 v83, v83
	v_add_f32_e32 v179, v179, v82
	v_add_f32_e32 v221, v221, v83
	v_cvt_pk_bf16_f32 v82, v82, v83
	s_waitcnt lgkmcnt(0)
	v_mfma_f32_32x32x16_bf16 v[98:113], v[184:187], v[130:133], 0
	ds_read_b64_tr_b16 v[200:201], v216 offset:9216
	ds_read_b64_tr_b16 v[202:203], v216 offset:9792
	ds_read_b64_tr_b16 v[204:205], v216 offset:9280
	ds_read_b64_tr_b16 v[206:207], v216 offset:9856
	v_exp_f32_e32 v84, v84
	v_exp_f32_e32 v85, v85
	v_add_f32_e32 v222, v222, v84
	v_add_f32_e32 v223, v223, v85
	v_cvt_pk_bf16_f32 v83, v84, v85
	v_mfma_f32_32x32x16_bf16 v[98:113], v[188:191], v[134:137], v[98:113]
	ds_read_b64_tr_b16 v[208:209], v216 offset:11520
	ds_read_b64_tr_b16 v[210:211], v216 offset:12096
	ds_read_b64_tr_b16 v[212:213], v216 offset:11584
	ds_read_b64_tr_b16 v[214:215], v216 offset:12160
	v_exp_f32_e32 v86, v86
	v_exp_f32_e32 v87, v87
	v_add_f32_e32 v179, v179, v86
	v_add_f32_e32 v221, v221, v87
	v_cvt_pk_bf16_f32 v84, v86, v87
	v_mfma_f32_32x32x16_bf16 v[98:113], v[192:195], v[146:149], v[98:113]
	v_exp_f32_e32 v88, v88
	v_exp_f32_e32 v89, v89
	v_add_f32_e32 v222, v222, v88
	v_add_f32_e32 v223, v223, v89
	v_cvt_pk_bf16_f32 v85, v88, v89
	v_mfma_f32_32x32x16_bf16 v[98:113], v[196:199], v[150:153], v[98:113]
	v_exp_f32_e32 v74, v74
	v_exp_f32_e32 v75, v75
	v_add_f32_e32 v178, v178, v74
	v_add_f32_e32 v218, v218, v75
	v_cvt_pk_bf16_f32 v74, v74, v75
	v_mfma_f32_32x32x16_bf16 v[114:129], v[184:187], v[154:157], 0
	v_exp_f32_e32 v76, v76
	v_exp_f32_e32 v77, v77
	v_add_f32_e32 v219, v219, v76
	v_add_f32_e32 v220, v220, v77
	v_cvt_pk_bf16_f32 v75, v76, v77
	v_mfma_f32_32x32x16_bf16 v[114:129], v[188:191], v[138:141], v[114:129]
	v_exp_f32_e32 v78, v78
	v_exp_f32_e32 v79, v79
	v_add_f32_e32 v178, v178, v78
	v_add_f32_e32 v218, v218, v79
	v_cvt_pk_bf16_f32 v76, v78, v79
	v_mfma_f32_32x32x16_bf16 v[114:129], v[192:195], v[142:145], v[114:129]
	v_exp_f32_e32 v80, v80
	v_exp_f32_e32 v81, v81
	v_add_f32_e32 v219, v219, v80
	v_add_f32_e32 v220, v220, v81
	v_cvt_pk_bf16_f32 v77, v80, v81
	v_mfma_f32_32x32x16_bf16 v[114:129], v[196:199], v[158:161], v[114:129]
	v_exp_f32_e32 v90, v90
	v_exp_f32_e32 v91, v91
	v_add_f32_e32 v179, v179, v90
	v_add_f32_e32 v221, v221, v91
	v_cvt_pk_bf16_f32 v90, v90, v91
	s_waitcnt lgkmcnt(4)
	v_mfma_f32_32x32x16_bf16 v[50:65], v[200:203], v[66:69], v[50:65]
	ds_read_b128 v[184:187], v183 offset:18432
	ds_read_b128 v[188:191], v183 offset:18464
	ds_read_b128 v[192:195], v183 offset:18496
	ds_read_b128 v[196:199], v183 offset:18528
	v_exp_f32_e32 v92, v92
	v_exp_f32_e32 v93, v93
	v_add_f32_e32 v222, v222, v92
	v_add_f32_e32 v223, v223, v93
	v_cvt_pk_bf16_f32 v91, v92, v93
	v_mfma_f32_32x32x16_bf16 v[34:49], v[204:207], v[66:69], v[34:49]
	v_exp_f32_e32 v94, v94
	v_exp_f32_e32 v95, v95
	v_add_f32_e32 v179, v179, v94
	v_add_f32_e32 v221, v221, v95
	v_cvt_pk_bf16_f32 v92, v94, v95
	v_mfma_f32_32x32x16_bf16 v[18:33], v[200:203], v[82:85], v[18:33]
	v_exp_f32_e32 v96, v96
	v_exp_f32_e32 v97, v97
	v_add_f32_e32 v222, v222, v96
	v_add_f32_e32 v223, v223, v97
	v_cvt_pk_bf16_f32 v93, v96, v97
	v_mfma_f32_32x32x16_bf16 v[2:17], v[204:207], v[82:85], v[2:17]
	v_exp_f32_e32 v98, v98
	v_exp_f32_e32 v99, v99
	v_add_f32_e32 v178, v178, v98
	v_add_f32_e32 v218, v218, v99
	v_cvt_pk_bf16_f32 v98, v98, v99
	s_waitcnt lgkmcnt(4)
	v_mfma_f32_32x32x16_bf16 v[50:65], v[208:211], v[74:77], v[50:65]
	ds_read_b64_tr_b16 v[200:201], v216 offset:13824
	ds_read_b64_tr_b16 v[202:203], v216 offset:14400
	ds_read_b64_tr_b16 v[204:205], v216 offset:13888
	ds_read_b64_tr_b16 v[206:207], v216 offset:14464
	v_exp_f32_e32 v100, v100
	v_exp_f32_e32 v101, v101
	v_add_f32_e32 v219, v219, v100
	v_add_f32_e32 v220, v220, v101
	v_cvt_pk_bf16_f32 v99, v100, v101
	v_mfma_f32_32x32x16_bf16 v[34:49], v[212:215], v[74:77], v[34:49]
	v_exp_f32_e32 v102, v102
	v_exp_f32_e32 v103, v103
	v_add_f32_e32 v178, v178, v102
	v_add_f32_e32 v218, v218, v103
	v_cvt_pk_bf16_f32 v100, v102, v103
	v_mfma_f32_32x32x16_bf16 v[18:33], v[208:211], v[90:93], v[18:33]
	v_exp_f32_e32 v104, v104
	v_exp_f32_e32 v105, v105
	v_add_f32_e32 v219, v219, v104
	v_add_f32_e32 v220, v220, v105
	v_cvt_pk_bf16_f32 v101, v104, v105
	v_mfma_f32_32x32x16_bf16 v[2:17], v[212:215], v[90:93], v[2:17]
	v_exp_f32_e32 v114, v114
	v_exp_f32_e32 v115, v115
	v_add_f32_e32 v179, v179, v114
	v_add_f32_e32 v221, v221, v115
	v_cvt_pk_bf16_f32 v114, v114, v115
	s_waitcnt lgkmcnt(4)
	v_mfma_f32_32x32x16_bf16 v[66:81], v[184:187], v[130:133], 0
	ds_read_b64_tr_b16 v[208:209], v216 offset:16128
	ds_read_b64_tr_b16 v[210:211], v216 offset:16704
	ds_read_b64_tr_b16 v[212:213], v216 offset:16192
	ds_read_b64_tr_b16 v[214:215], v216 offset:16768
	v_exp_f32_e32 v116, v116
	v_exp_f32_e32 v117, v117
	v_add_f32_e32 v222, v222, v116
	v_add_f32_e32 v223, v223, v117
	v_cvt_pk_bf16_f32 v115, v116, v117
	v_mfma_f32_32x32x16_bf16 v[66:81], v[188:191], v[134:137], v[66:81]
	v_exp_f32_e32 v118, v118
	v_exp_f32_e32 v119, v119
	v_add_f32_e32 v179, v179, v118
	v_add_f32_e32 v221, v221, v119
	v_cvt_pk_bf16_f32 v116, v118, v119
	v_mfma_f32_32x32x16_bf16 v[66:81], v[192:195], v[146:149], v[66:81]
	v_exp_f32_e32 v120, v120
	v_exp_f32_e32 v121, v121
	v_add_f32_e32 v222, v222, v120
	v_add_f32_e32 v223, v223, v121
	v_cvt_pk_bf16_f32 v117, v120, v121
	v_mfma_f32_32x32x16_bf16 v[66:81], v[196:199], v[150:153], v[66:81]
	v_exp_f32_e32 v106, v106
	v_exp_f32_e32 v107, v107
	v_add_f32_e32 v178, v178, v106
	v_add_f32_e32 v218, v218, v107
	v_cvt_pk_bf16_f32 v106, v106, v107
	s_waitcnt lgkmcnt(4)
	v_mfma_f32_32x32x16_bf16 v[50:65], v[200:203], v[98:101], v[50:65]
	v_exp_f32_e32 v108, v108
	v_exp_f32_e32 v109, v109
	v_add_f32_e32 v219, v219, v108
	v_add_f32_e32 v220, v220, v109
	v_cvt_pk_bf16_f32 v107, v108, v109
	v_mfma_f32_32x32x16_bf16 v[34:49], v[204:207], v[98:101], v[34:49]
	v_exp_f32_e32 v110, v110
	v_exp_f32_e32 v111, v111
	v_add_f32_e32 v178, v178, v110
	v_add_f32_e32 v218, v218, v111
	v_cvt_pk_bf16_f32 v108, v110, v111
	v_mfma_f32_32x32x16_bf16 v[18:33], v[200:203], v[114:117], v[18:33]
	s_waitcnt vmcnt(0)
	ds_write_b128 v228, v[162:165]
	ds_write_b128 v228, v[166:169] offset:9216
	v_exp_f32_e32 v112, v112
	v_exp_f32_e32 v113, v113
	v_add_f32_e32 v219, v219, v112
	v_add_f32_e32 v220, v220, v113
	v_cvt_pk_bf16_f32 v109, v112, v113
	v_mfma_f32_32x32x16_bf16 v[2:17], v[204:207], v[114:117], v[2:17]
	v_exp_f32_e32 v122, v122
	v_exp_f32_e32 v123, v123
	v_add_f32_e32 v179, v179, v122
	v_add_f32_e32 v221, v221, v123
	v_cvt_pk_bf16_f32 v122, v122, v123
	v_mfma_f32_32x32x16_bf16 v[82:97], v[184:187], v[154:157], 0
	v_exp_f32_e32 v124, v124
	v_exp_f32_e32 v125, v125
	v_add_f32_e32 v222, v222, v124
	v_add_f32_e32 v223, v223, v125
	v_cvt_pk_bf16_f32 v123, v124, v125
	v_mfma_f32_32x32x16_bf16 v[82:97], v[188:191], v[138:141], v[82:97]
	v_exp_f32_e32 v126, v126
	v_exp_f32_e32 v127, v127
	v_add_f32_e32 v179, v179, v126
	v_add_f32_e32 v221, v221, v127
	v_cvt_pk_bf16_f32 v124, v126, v127
	v_mfma_f32_32x32x16_bf16 v[82:97], v[192:195], v[142:145], v[82:97]
	v_exp_f32_e32 v128, v128
	v_exp_f32_e32 v129, v129
	v_add_f32_e32 v222, v222, v128
	v_add_f32_e32 v223, v223, v129
	v_cvt_pk_bf16_f32 v125, v128, v129
	v_mfma_f32_32x32x16_bf16 v[82:97], v[196:199], v[158:161], v[82:97]
	ds_read_b128 v[184:187], v183 offset:23040
	ds_read_b128 v[188:191], v183 offset:23072
	ds_read_b128 v[192:195], v183 offset:23104
	ds_read_b128 v[196:199], v183 offset:23136
	v_exp_f32_e32 v66, v66
	v_exp_f32_e32 v67, v67
	v_add_f32_e32 v178, v178, v66
	v_add_f32_e32 v218, v218, v67
	v_cvt_pk_bf16_f32 v66, v66, v67
	s_waitcnt lgkmcnt(6)
	v_mfma_f32_32x32x16_bf16 v[50:65], v[208:211], v[106:109], v[50:65]
	v_exp_f32_e32 v68, v68
	v_exp_f32_e32 v69, v69
	v_add_f32_e32 v219, v219, v68
	v_add_f32_e32 v220, v220, v69
	v_cvt_pk_bf16_f32 v67, v68, v69
	v_mfma_f32_32x32x16_bf16 v[34:49], v[212:215], v[106:109], v[34:49]
	v_exp_f32_e32 v70, v70
	v_exp_f32_e32 v71, v71
	v_add_f32_e32 v178, v178, v70
	v_add_f32_e32 v218, v218, v71
	v_cvt_pk_bf16_f32 v68, v70, v71
	v_mfma_f32_32x32x16_bf16 v[18:33], v[208:211], v[122:125], v[18:33]
	v_exp_f32_e32 v72, v72
	v_exp_f32_e32 v73, v73
	v_add_f32_e32 v219, v219, v72
	v_add_f32_e32 v220, v220, v73
	v_cvt_pk_bf16_f32 v69, v72, v73
	v_mfma_f32_32x32x16_bf16 v[2:17], v[212:215], v[122:125], v[2:17]
	v_exp_f32_e32 v82, v82
	v_exp_f32_e32 v83, v83
	v_add_f32_e32 v179, v179, v82
	v_add_f32_e32 v221, v221, v83
	v_cvt_pk_bf16_f32 v82, v82, v83
	s_waitcnt lgkmcnt(0)
	v_mfma_f32_32x32x16_bf16 v[98:113], v[184:187], v[130:133], 0
	ds_read_b64_tr_b16 v[200:201], v216 offset:27648
	ds_read_b64_tr_b16 v[202:203], v216 offset:28224
	ds_read_b64_tr_b16 v[204:205], v216 offset:27712
	ds_read_b64_tr_b16 v[206:207], v216 offset:28288
	v_exp_f32_e32 v84, v84
	v_exp_f32_e32 v85, v85
	v_add_f32_e32 v222, v222, v84
	v_add_f32_e32 v223, v223, v85
	v_cvt_pk_bf16_f32 v83, v84, v85
	v_mfma_f32_32x32x16_bf16 v[98:113], v[188:191], v[134:137], v[98:113]
	ds_read_b64_tr_b16 v[208:209], v216 offset:29952
	ds_read_b64_tr_b16 v[210:211], v216 offset:30528
	ds_read_b64_tr_b16 v[212:213], v216 offset:30016
	ds_read_b64_tr_b16 v[214:215], v216 offset:30592
	v_exp_f32_e32 v86, v86
	v_exp_f32_e32 v87, v87
	v_add_f32_e32 v179, v179, v86
	v_add_f32_e32 v221, v221, v87
	v_cvt_pk_bf16_f32 v84, v86, v87
	v_mfma_f32_32x32x16_bf16 v[98:113], v[192:195], v[146:149], v[98:113]
	v_exp_f32_e32 v88, v88
	v_exp_f32_e32 v89, v89
	v_add_f32_e32 v222, v222, v88
	v_add_f32_e32 v223, v223, v89
	v_cvt_pk_bf16_f32 v85, v88, v89
	v_mfma_f32_32x32x16_bf16 v[98:113], v[196:199], v[150:153], v[98:113]
	v_exp_f32_e32 v74, v74
	v_exp_f32_e32 v75, v75
	v_add_f32_e32 v178, v178, v74
	v_add_f32_e32 v218, v218, v75
	v_cvt_pk_bf16_f32 v74, v74, v75
	v_mfma_f32_32x32x16_bf16 v[114:129], v[184:187], v[154:157], 0
	v_exp_f32_e32 v76, v76
	v_exp_f32_e32 v77, v77
	v_add_f32_e32 v219, v219, v76
	v_add_f32_e32 v220, v220, v77
	v_cvt_pk_bf16_f32 v75, v76, v77
	v_mfma_f32_32x32x16_bf16 v[114:129], v[188:191], v[138:141], v[114:129]
	v_exp_f32_e32 v78, v78
	v_exp_f32_e32 v79, v79
	v_add_f32_e32 v178, v178, v78
	v_add_f32_e32 v218, v218, v79
	v_cvt_pk_bf16_f32 v76, v78, v79
	v_mfma_f32_32x32x16_bf16 v[114:129], v[192:195], v[142:145], v[114:129]
	v_exp_f32_e32 v80, v80
	v_exp_f32_e32 v81, v81
	v_add_f32_e32 v219, v219, v80
	v_add_f32_e32 v220, v220, v81
	v_cvt_pk_bf16_f32 v77, v80, v81
	v_mfma_f32_32x32x16_bf16 v[114:129], v[196:199], v[158:161], v[114:129]
	v_exp_f32_e32 v90, v90
	v_exp_f32_e32 v91, v91
	v_add_f32_e32 v179, v179, v90
	v_add_f32_e32 v221, v221, v91
	v_cvt_pk_bf16_f32 v90, v90, v91
	s_waitcnt lgkmcnt(4)
	v_mfma_f32_32x32x16_bf16 v[50:65], v[200:203], v[66:69], v[50:65]
	ds_read_b128 v[184:187], v183 offset:36864
	ds_read_b128 v[188:191], v183 offset:36896
	ds_read_b128 v[192:195], v183 offset:36928
	ds_read_b128 v[196:199], v183 offset:36960
	v_exp_f32_e32 v92, v92
	v_exp_f32_e32 v93, v93
	v_add_f32_e32 v222, v222, v92
	v_add_f32_e32 v223, v223, v93
	v_cvt_pk_bf16_f32 v91, v92, v93
	v_mfma_f32_32x32x16_bf16 v[34:49], v[204:207], v[66:69], v[34:49]
	v_exp_f32_e32 v94, v94
	v_exp_f32_e32 v95, v95
	v_add_f32_e32 v179, v179, v94
	v_add_f32_e32 v221, v221, v95
	v_cvt_pk_bf16_f32 v92, v94, v95
	v_mfma_f32_32x32x16_bf16 v[18:33], v[200:203], v[82:85], v[18:33]
	v_exp_f32_e32 v96, v96
	v_exp_f32_e32 v97, v97
	v_add_f32_e32 v222, v222, v96
	v_add_f32_e32 v223, v223, v97
	v_cvt_pk_bf16_f32 v93, v96, v97
	v_mfma_f32_32x32x16_bf16 v[2:17], v[204:207], v[82:85], v[2:17]
	v_exp_f32_e32 v98, v98
	v_exp_f32_e32 v99, v99
	v_add_f32_e32 v178, v178, v98
	v_add_f32_e32 v218, v218, v99
	v_cvt_pk_bf16_f32 v98, v98, v99
	s_waitcnt lgkmcnt(4)
	v_mfma_f32_32x32x16_bf16 v[50:65], v[208:211], v[74:77], v[50:65]
	ds_read_b64_tr_b16 v[200:201], v216 offset:32256
	ds_read_b64_tr_b16 v[202:203], v216 offset:32832
	ds_read_b64_tr_b16 v[204:205], v216 offset:32320
	ds_read_b64_tr_b16 v[206:207], v216 offset:32896
	v_exp_f32_e32 v100, v100
	v_exp_f32_e32 v101, v101
	v_add_f32_e32 v219, v219, v100
	v_add_f32_e32 v220, v220, v101
	v_cvt_pk_bf16_f32 v99, v100, v101
	v_mfma_f32_32x32x16_bf16 v[34:49], v[212:215], v[74:77], v[34:49]
	v_exp_f32_e32 v102, v102
	v_exp_f32_e32 v103, v103
	v_add_f32_e32 v178, v178, v102
	v_add_f32_e32 v218, v218, v103
	v_cvt_pk_bf16_f32 v100, v102, v103
	v_mfma_f32_32x32x16_bf16 v[18:33], v[208:211], v[90:93], v[18:33]
	v_exp_f32_e32 v104, v104
	v_exp_f32_e32 v105, v105
	v_add_f32_e32 v219, v219, v104
	v_add_f32_e32 v220, v220, v105
	v_cvt_pk_bf16_f32 v101, v104, v105
	v_mfma_f32_32x32x16_bf16 v[2:17], v[212:215], v[90:93], v[2:17]
	v_exp_f32_e32 v114, v114
	v_exp_f32_e32 v115, v115
	v_add_f32_e32 v179, v179, v114
	v_add_f32_e32 v221, v221, v115
	v_cvt_pk_bf16_f32 v114, v114, v115
	s_waitcnt lgkmcnt(4)
	v_mfma_f32_32x32x16_bf16 v[66:81], v[184:187], v[130:133], 0
	ds_read_b64_tr_b16 v[208:209], v216 offset:34560
	ds_read_b64_tr_b16 v[210:211], v216 offset:35136
	ds_read_b64_tr_b16 v[212:213], v216 offset:34624
	ds_read_b64_tr_b16 v[214:215], v216 offset:35200
	v_exp_f32_e32 v116, v116
	v_exp_f32_e32 v117, v117
	v_add_f32_e32 v222, v222, v116
	v_add_f32_e32 v223, v223, v117
	v_cvt_pk_bf16_f32 v115, v116, v117
	v_mfma_f32_32x32x16_bf16 v[66:81], v[188:191], v[134:137], v[66:81]
	v_exp_f32_e32 v118, v118
	v_exp_f32_e32 v119, v119
	v_add_f32_e32 v179, v179, v118
	v_add_f32_e32 v221, v221, v119
	v_cvt_pk_bf16_f32 v116, v118, v119
	v_mfma_f32_32x32x16_bf16 v[66:81], v[192:195], v[146:149], v[66:81]
	v_exp_f32_e32 v120, v120
	v_exp_f32_e32 v121, v121
	v_add_f32_e32 v222, v222, v120
	v_add_f32_e32 v223, v223, v121
	v_cvt_pk_bf16_f32 v117, v120, v121
	v_mfma_f32_32x32x16_bf16 v[66:81], v[196:199], v[150:153], v[66:81]
	v_exp_f32_e32 v106, v106
	v_exp_f32_e32 v107, v107
	v_add_f32_e32 v178, v178, v106
	v_add_f32_e32 v218, v218, v107
	v_cvt_pk_bf16_f32 v106, v106, v107
	s_waitcnt lgkmcnt(4)
	v_mfma_f32_32x32x16_bf16 v[50:65], v[200:203], v[98:101], v[50:65]
	v_exp_f32_e32 v108, v108
	v_exp_f32_e32 v109, v109
	v_add_f32_e32 v219, v219, v108
	v_add_f32_e32 v220, v220, v109
	v_cvt_pk_bf16_f32 v107, v108, v109
	v_mfma_f32_32x32x16_bf16 v[34:49], v[204:207], v[98:101], v[34:49]
	v_exp_f32_e32 v110, v110
	v_exp_f32_e32 v111, v111
	v_add_f32_e32 v178, v178, v110
	v_add_f32_e32 v218, v218, v111
	v_cvt_pk_bf16_f32 v108, v110, v111
	v_mfma_f32_32x32x16_bf16 v[18:33], v[200:203], v[114:117], v[18:33]
	v_exp_f32_e32 v112, v112
	v_exp_f32_e32 v113, v113
	v_add_f32_e32 v219, v219, v112
	v_add_f32_e32 v220, v220, v113
	v_cvt_pk_bf16_f32 v109, v112, v113
	v_mfma_f32_32x32x16_bf16 v[2:17], v[204:207], v[114:117], v[2:17]
	v_exp_f32_e32 v122, v122
	v_exp_f32_e32 v123, v123
	v_add_f32_e32 v179, v179, v122
	v_add_f32_e32 v221, v221, v123
	v_cvt_pk_bf16_f32 v122, v122, v123
	v_mfma_f32_32x32x16_bf16 v[82:97], v[184:187], v[154:157], 0
	v_exp_f32_e32 v124, v124
	v_exp_f32_e32 v125, v125
	v_add_f32_e32 v222, v222, v124
	v_add_f32_e32 v223, v223, v125
	v_cvt_pk_bf16_f32 v123, v124, v125
	v_mfma_f32_32x32x16_bf16 v[82:97], v[188:191], v[138:141], v[82:97]
	v_exp_f32_e32 v126, v126
	v_exp_f32_e32 v127, v127
	v_add_f32_e32 v179, v179, v126
	v_add_f32_e32 v221, v221, v127
	v_cvt_pk_bf16_f32 v124, v126, v127
	v_mfma_f32_32x32x16_bf16 v[82:97], v[192:195], v[142:145], v[82:97]
	v_exp_f32_e32 v128, v128
	v_exp_f32_e32 v129, v129
	v_add_f32_e32 v222, v222, v128
	v_add_f32_e32 v223, v223, v129
	v_cvt_pk_bf16_f32 v125, v128, v129
	v_mfma_f32_32x32x16_bf16 v[82:97], v[196:199], v[158:161], v[82:97]
	s_waitcnt lgkmcnt(0)
	s_barrier
	ds_read_b128 v[184:187], v183 offset:41472
	ds_read_b128 v[188:191], v183 offset:41504
	ds_read_b128 v[192:195], v183 offset:41536
	ds_read_b128 v[196:199], v183 offset:41568
	v_exp_f32_e32 v66, v66
	v_exp_f32_e32 v67, v67
	v_add_f32_e32 v178, v178, v66
	v_add_f32_e32 v218, v218, v67
	v_cvt_pk_bf16_f32 v66, v66, v67
	v_mfma_f32_32x32x16_bf16 v[50:65], v[208:211], v[106:109], v[50:65]
	v_exp_f32_e32 v68, v68
	v_exp_f32_e32 v69, v69
	v_add_f32_e32 v219, v219, v68
	v_add_f32_e32 v220, v220, v69
	v_cvt_pk_bf16_f32 v67, v68, v69
	v_mfma_f32_32x32x16_bf16 v[34:49], v[212:215], v[106:109], v[34:49]
	v_exp_f32_e32 v70, v70
	v_exp_f32_e32 v71, v71
	v_add_f32_e32 v178, v178, v70
	v_add_f32_e32 v218, v218, v71
	v_cvt_pk_bf16_f32 v68, v70, v71
	v_mfma_f32_32x32x16_bf16 v[18:33], v[208:211], v[122:125], v[18:33]
	v_exp_f32_e32 v72, v72
	v_exp_f32_e32 v73, v73
	v_add_f32_e32 v219, v219, v72
	v_add_f32_e32 v220, v220, v73
	v_cvt_pk_bf16_f32 v69, v72, v73
	v_mfma_f32_32x32x16_bf16 v[2:17], v[212:215], v[122:125], v[2:17]
	v_exp_f32_e32 v82, v82
	v_exp_f32_e32 v83, v83
	v_add_f32_e32 v179, v179, v82
	v_add_f32_e32 v221, v221, v83
	v_cvt_pk_bf16_f32 v82, v82, v83
	s_waitcnt lgkmcnt(0)
	v_mfma_f32_32x32x16_bf16 v[98:113], v[184:187], v[130:133], 0
	ds_read_b64_tr_b16 v[200:201], v216 offset:46080
	ds_read_b64_tr_b16 v[202:203], v216 offset:46656
	ds_read_b64_tr_b16 v[204:205], v216 offset:46144
	ds_read_b64_tr_b16 v[206:207], v216 offset:46720
	v_exp_f32_e32 v84, v84
	v_exp_f32_e32 v85, v85
	v_add_f32_e32 v222, v222, v84
	v_add_f32_e32 v223, v223, v85
	v_cvt_pk_bf16_f32 v83, v84, v85
	v_mfma_f32_32x32x16_bf16 v[98:113], v[188:191], v[134:137], v[98:113]
	ds_read_b64_tr_b16 v[208:209], v216 offset:48384
	ds_read_b64_tr_b16 v[210:211], v216 offset:48960
	ds_read_b64_tr_b16 v[212:213], v216 offset:48448
	ds_read_b64_tr_b16 v[214:215], v216 offset:49024
	v_exp_f32_e32 v86, v86
	v_exp_f32_e32 v87, v87
	v_add_f32_e32 v179, v179, v86
	v_add_f32_e32 v221, v221, v87
	v_cvt_pk_bf16_f32 v84, v86, v87
	v_mfma_f32_32x32x16_bf16 v[98:113], v[192:195], v[146:149], v[98:113]
	v_exp_f32_e32 v88, v88
	v_exp_f32_e32 v89, v89
	v_add_f32_e32 v222, v222, v88
	v_add_f32_e32 v223, v223, v89
	v_cvt_pk_bf16_f32 v85, v88, v89
	v_mfma_f32_32x32x16_bf16 v[98:113], v[196:199], v[150:153], v[98:113]
	v_exp_f32_e32 v74, v74
	v_exp_f32_e32 v75, v75
	v_add_f32_e32 v178, v178, v74
	v_add_f32_e32 v218, v218, v75
	v_cvt_pk_bf16_f32 v74, v74, v75
	v_mfma_f32_32x32x16_bf16 v[114:129], v[184:187], v[154:157], 0
	v_exp_f32_e32 v76, v76
	v_exp_f32_e32 v77, v77
	v_add_f32_e32 v219, v219, v76
	v_add_f32_e32 v220, v220, v77
	v_cvt_pk_bf16_f32 v75, v76, v77
	v_mfma_f32_32x32x16_bf16 v[114:129], v[188:191], v[138:141], v[114:129]
	v_exp_f32_e32 v78, v78
	v_exp_f32_e32 v79, v79
	v_add_f32_e32 v178, v178, v78
	v_add_f32_e32 v218, v218, v79
	v_cvt_pk_bf16_f32 v76, v78, v79
	v_mfma_f32_32x32x16_bf16 v[114:129], v[192:195], v[142:145], v[114:129]
	v_exp_f32_e32 v80, v80
	v_exp_f32_e32 v81, v81
	v_add_f32_e32 v219, v219, v80
	v_add_f32_e32 v220, v220, v81
	v_cvt_pk_bf16_f32 v77, v80, v81
	v_mfma_f32_32x32x16_bf16 v[114:129], v[196:199], v[158:161], v[114:129]
	v_exp_f32_e32 v90, v90
	v_exp_f32_e32 v91, v91
	v_add_f32_e32 v179, v179, v90
	v_add_f32_e32 v221, v221, v91
	v_cvt_pk_bf16_f32 v90, v90, v91
	s_waitcnt lgkmcnt(4)
	v_mfma_f32_32x32x16_bf16 v[50:65], v[200:203], v[66:69], v[50:65]
	ds_read_b128 v[184:187], v226
	ds_read_b128 v[188:191], v226 offset:32
	ds_read_b128 v[192:195], v226 offset:64
	ds_read_b128 v[196:199], v226 offset:96
	v_exp_f32_e32 v92, v92
	v_exp_f32_e32 v93, v93
	v_add_f32_e32 v222, v222, v92
	v_add_f32_e32 v223, v223, v93
	v_cvt_pk_bf16_f32 v91, v92, v93
	v_mfma_f32_32x32x16_bf16 v[34:49], v[204:207], v[66:69], v[34:49]
	v_exp_f32_e32 v94, v94
	v_exp_f32_e32 v95, v95
	v_add_f32_e32 v179, v179, v94
	v_add_f32_e32 v221, v221, v95
	v_cvt_pk_bf16_f32 v92, v94, v95
	v_mfma_f32_32x32x16_bf16 v[18:33], v[200:203], v[82:85], v[18:33]
	v_exp_f32_e32 v96, v96
	v_exp_f32_e32 v97, v97
	v_add_f32_e32 v222, v222, v96
	v_add_f32_e32 v223, v223, v97
	v_cvt_pk_bf16_f32 v93, v96, v97
	v_mfma_f32_32x32x16_bf16 v[2:17], v[204:207], v[82:85], v[2:17]
	v_exp_f32_e32 v98, v98
	v_exp_f32_e32 v99, v99
	v_add_f32_e32 v178, v178, v98
	v_add_f32_e32 v218, v218, v99
	v_cvt_pk_bf16_f32 v98, v98, v99
	s_waitcnt lgkmcnt(4)
	v_mfma_f32_32x32x16_bf16 v[50:65], v[208:211], v[74:77], v[50:65]
	ds_read_b64_tr_b16 v[200:201], v216 offset:50688
	ds_read_b64_tr_b16 v[202:203], v216 offset:51264
	ds_read_b64_tr_b16 v[204:205], v216 offset:50752
	ds_read_b64_tr_b16 v[206:207], v216 offset:51328
	v_exp_f32_e32 v100, v100
	v_exp_f32_e32 v101, v101
	v_add_f32_e32 v219, v219, v100
	v_add_f32_e32 v220, v220, v101
	v_cvt_pk_bf16_f32 v99, v100, v101
	v_mfma_f32_32x32x16_bf16 v[34:49], v[212:215], v[74:77], v[34:49]
	v_exp_f32_e32 v102, v102
	v_exp_f32_e32 v103, v103
	v_add_f32_e32 v178, v178, v102
	v_add_f32_e32 v218, v218, v103
	v_cvt_pk_bf16_f32 v100, v102, v103
	v_mfma_f32_32x32x16_bf16 v[18:33], v[208:211], v[90:93], v[18:33]
	v_exp_f32_e32 v104, v104
	v_exp_f32_e32 v105, v105
	v_add_f32_e32 v219, v219, v104
	v_add_f32_e32 v220, v220, v105
	v_cvt_pk_bf16_f32 v101, v104, v105
	v_mfma_f32_32x32x16_bf16 v[2:17], v[212:215], v[90:93], v[2:17]
	v_exp_f32_e32 v114, v114
	v_exp_f32_e32 v115, v115
	v_add_f32_e32 v179, v179, v114
	v_add_f32_e32 v221, v221, v115
	v_cvt_pk_bf16_f32 v114, v114, v115
	s_waitcnt lgkmcnt(4)
	v_mfma_f32_32x32x16_bf16 v[66:81], v[184:187], v[130:133], 0
	ds_read_b64_tr_b16 v[208:209], v216 offset:52992
	ds_read_b64_tr_b16 v[210:211], v216 offset:53568
	ds_read_b64_tr_b16 v[212:213], v216 offset:53056
	ds_read_b64_tr_b16 v[214:215], v216 offset:53632
	v_exp_f32_e32 v116, v116
	v_exp_f32_e32 v117, v117
	v_add_f32_e32 v222, v222, v116
	v_add_f32_e32 v223, v223, v117
	v_cvt_pk_bf16_f32 v115, v116, v117
	v_mfma_f32_32x32x16_bf16 v[66:81], v[188:191], v[134:137], v[66:81]
	v_exp_f32_e32 v118, v118
	v_exp_f32_e32 v119, v119
	v_add_f32_e32 v179, v179, v118
	v_add_f32_e32 v221, v221, v119
	v_cvt_pk_bf16_f32 v116, v118, v119
	v_mfma_f32_32x32x16_bf16 v[66:81], v[192:195], v[146:149], v[66:81]
	v_exp_f32_e32 v120, v120
	v_exp_f32_e32 v121, v121
	v_add_f32_e32 v222, v222, v120
	v_add_f32_e32 v223, v223, v121
	v_cvt_pk_bf16_f32 v117, v120, v121
	v_mfma_f32_32x32x16_bf16 v[66:81], v[196:199], v[150:153], v[66:81]
	v_exp_f32_e32 v106, v106
	v_exp_f32_e32 v107, v107
	v_add_f32_e32 v178, v178, v106
	v_add_f32_e32 v218, v218, v107
	v_cvt_pk_bf16_f32 v106, v106, v107
	s_waitcnt lgkmcnt(4)
	v_mfma_f32_32x32x16_bf16 v[50:65], v[200:203], v[98:101], v[50:65]
	v_exp_f32_e32 v108, v108
	v_exp_f32_e32 v109, v109
	v_add_f32_e32 v219, v219, v108
	v_add_f32_e32 v220, v220, v109
	v_cvt_pk_bf16_f32 v107, v108, v109
	v_mfma_f32_32x32x16_bf16 v[34:49], v[204:207], v[98:101], v[34:49]
	v_exp_f32_e32 v110, v110
	v_exp_f32_e32 v111, v111
	v_add_f32_e32 v178, v178, v110
	v_add_f32_e32 v218, v218, v111
	v_cvt_pk_bf16_f32 v108, v110, v111
	v_mfma_f32_32x32x16_bf16 v[18:33], v[200:203], v[114:117], v[18:33]
	v_exp_f32_e32 v112, v112
	v_exp_f32_e32 v113, v113
	v_add_f32_e32 v219, v219, v112
	v_add_f32_e32 v220, v220, v113
	v_cvt_pk_bf16_f32 v109, v112, v113
	v_mfma_f32_32x32x16_bf16 v[2:17], v[204:207], v[114:117], v[2:17]
	v_exp_f32_e32 v122, v122
	v_exp_f32_e32 v123, v123
	v_add_f32_e32 v179, v179, v122
	v_add_f32_e32 v221, v221, v123
	v_cvt_pk_bf16_f32 v122, v122, v123
	v_mfma_f32_32x32x16_bf16 v[82:97], v[184:187], v[154:157], 0
	v_exp_f32_e32 v124, v124
	v_exp_f32_e32 v125, v125
	v_add_f32_e32 v222, v222, v124
	v_add_f32_e32 v223, v223, v125
	v_cvt_pk_bf16_f32 v123, v124, v125
	v_mfma_f32_32x32x16_bf16 v[82:97], v[188:191], v[138:141], v[82:97]
	v_exp_f32_e32 v126, v126
	v_exp_f32_e32 v127, v127
	v_add_f32_e32 v179, v179, v126
	v_add_f32_e32 v221, v221, v127
	v_cvt_pk_bf16_f32 v124, v126, v127
	v_mfma_f32_32x32x16_bf16 v[82:97], v[192:195], v[142:145], v[82:97]
	v_exp_f32_e32 v128, v128
	v_exp_f32_e32 v129, v129
	v_add_f32_e32 v222, v222, v128
	v_add_f32_e32 v223, v223, v129
	v_cvt_pk_bf16_f32 v125, v128, v129
	v_mfma_f32_32x32x16_bf16 v[82:97], v[196:199], v[158:161], v[82:97]
	ds_read_b128 v[184:187], v226 offset:4608
	ds_read_b128 v[188:191], v226 offset:4640
	ds_read_b128 v[192:195], v226 offset:4672
	ds_read_b128 v[196:199], v226 offset:4704
	v_exp_f32_e32 v66, v66
	v_exp_f32_e32 v67, v67
	v_add_f32_e32 v178, v178, v66
	v_add_f32_e32 v218, v218, v67
	v_cvt_pk_bf16_f32 v66, v66, v67
	s_waitcnt lgkmcnt(4)
	v_mfma_f32_32x32x16_bf16 v[50:65], v[208:211], v[106:109], v[50:65]
	v_exp_f32_e32 v68, v68
	v_exp_f32_e32 v69, v69
	v_add_f32_e32 v219, v219, v68
	v_add_f32_e32 v220, v220, v69
	v_cvt_pk_bf16_f32 v67, v68, v69
	v_mfma_f32_32x32x16_bf16 v[34:49], v[212:215], v[106:109], v[34:49]
	v_exp_f32_e32 v70, v70
	v_exp_f32_e32 v71, v71
	v_add_f32_e32 v178, v178, v70
	v_add_f32_e32 v218, v218, v71
	v_cvt_pk_bf16_f32 v68, v70, v71
	v_mfma_f32_32x32x16_bf16 v[18:33], v[208:211], v[122:125], v[18:33]
	v_exp_f32_e32 v72, v72
	v_exp_f32_e32 v73, v73
	v_add_f32_e32 v219, v219, v72
	v_add_f32_e32 v220, v220, v73
	v_cvt_pk_bf16_f32 v69, v72, v73
	v_mfma_f32_32x32x16_bf16 v[2:17], v[212:215], v[122:125], v[2:17]
	v_exp_f32_e32 v82, v82
	v_exp_f32_e32 v83, v83
	v_add_f32_e32 v179, v179, v82
	v_add_f32_e32 v221, v221, v83
	v_cvt_pk_bf16_f32 v82, v82, v83
	s_waitcnt lgkmcnt(0)
	v_mfma_f32_32x32x16_bf16 v[98:113], v[184:187], v[130:133], 0
	ds_read_b64_tr_b16 v[200:201], v227 offset:9216
	ds_read_b64_tr_b16 v[202:203], v227 offset:9792
	ds_read_b64_tr_b16 v[204:205], v227 offset:9280
	ds_read_b64_tr_b16 v[206:207], v227 offset:9856
	v_exp_f32_e32 v84, v84
	v_exp_f32_e32 v85, v85
	v_add_f32_e32 v222, v222, v84
	v_add_f32_e32 v223, v223, v85
	v_cvt_pk_bf16_f32 v83, v84, v85
	v_mfma_f32_32x32x16_bf16 v[98:113], v[188:191], v[134:137], v[98:113]
	ds_read_b64_tr_b16 v[208:209], v227 offset:11520
	ds_read_b64_tr_b16 v[210:211], v227 offset:12096
	ds_read_b64_tr_b16 v[212:213], v227 offset:11584
	ds_read_b64_tr_b16 v[214:215], v227 offset:12160
	v_exp_f32_e32 v86, v86
	v_exp_f32_e32 v87, v87
	v_add_f32_e32 v179, v179, v86
	v_add_f32_e32 v221, v221, v87
	v_cvt_pk_bf16_f32 v84, v86, v87
	v_mfma_f32_32x32x16_bf16 v[98:113], v[192:195], v[146:149], v[98:113]
	v_exp_f32_e32 v88, v88
	v_exp_f32_e32 v89, v89
	v_add_f32_e32 v222, v222, v88
	v_add_f32_e32 v223, v223, v89
	v_cvt_pk_bf16_f32 v85, v88, v89
	v_mfma_f32_32x32x16_bf16 v[98:113], v[196:199], v[150:153], v[98:113]
	v_exp_f32_e32 v74, v74
	v_exp_f32_e32 v75, v75
	v_add_f32_e32 v178, v178, v74
	v_add_f32_e32 v218, v218, v75
	v_cvt_pk_bf16_f32 v74, v74, v75
	v_mfma_f32_32x32x16_bf16 v[114:129], v[184:187], v[154:157], 0
	v_exp_f32_e32 v76, v76
	v_exp_f32_e32 v77, v77
	v_add_f32_e32 v219, v219, v76
	v_add_f32_e32 v220, v220, v77
	v_cvt_pk_bf16_f32 v75, v76, v77
	v_mfma_f32_32x32x16_bf16 v[114:129], v[188:191], v[138:141], v[114:129]
	v_exp_f32_e32 v78, v78
	v_exp_f32_e32 v79, v79
	v_add_f32_e32 v178, v178, v78
	v_add_f32_e32 v218, v218, v79
	v_cvt_pk_bf16_f32 v76, v78, v79
	v_mfma_f32_32x32x16_bf16 v[114:129], v[192:195], v[142:145], v[114:129]
	v_exp_f32_e32 v80, v80
	v_exp_f32_e32 v81, v81
	v_add_f32_e32 v219, v219, v80
	v_add_f32_e32 v220, v220, v81
	v_cvt_pk_bf16_f32 v77, v80, v81
	v_mfma_f32_32x32x16_bf16 v[114:129], v[196:199], v[158:161], v[114:129]
	v_exp_f32_e32 v90, v90
	v_exp_f32_e32 v91, v91
	v_add_f32_e32 v179, v179, v90
	v_add_f32_e32 v221, v221, v91
	v_cvt_pk_bf16_f32 v90, v90, v91
	s_waitcnt lgkmcnt(4)
	v_mfma_f32_32x32x16_bf16 v[50:65], v[200:203], v[66:69], v[50:65]
	ds_read_b128 v[184:187], v226 offset:18432
	ds_read_b128 v[188:191], v226 offset:18464
	ds_read_b128 v[192:195], v226 offset:18496
	ds_read_b128 v[196:199], v226 offset:18528
	v_exp_f32_e32 v92, v92
	v_exp_f32_e32 v93, v93
	v_add_f32_e32 v222, v222, v92
	v_add_f32_e32 v223, v223, v93
	v_cvt_pk_bf16_f32 v91, v92, v93
	v_mfma_f32_32x32x16_bf16 v[34:49], v[204:207], v[66:69], v[34:49]
	v_exp_f32_e32 v94, v94
	v_exp_f32_e32 v95, v95
	v_add_f32_e32 v179, v179, v94
	v_add_f32_e32 v221, v221, v95
	v_cvt_pk_bf16_f32 v92, v94, v95
	v_mfma_f32_32x32x16_bf16 v[18:33], v[200:203], v[82:85], v[18:33]
	v_exp_f32_e32 v96, v96
	v_exp_f32_e32 v97, v97
	v_add_f32_e32 v222, v222, v96
	v_add_f32_e32 v223, v223, v97
	v_cvt_pk_bf16_f32 v93, v96, v97
	v_mfma_f32_32x32x16_bf16 v[2:17], v[204:207], v[82:85], v[2:17]
	v_exp_f32_e32 v98, v98
	v_exp_f32_e32 v99, v99
	v_add_f32_e32 v178, v178, v98
	v_add_f32_e32 v218, v218, v99
	v_cvt_pk_bf16_f32 v98, v98, v99
	s_waitcnt lgkmcnt(4)
	v_mfma_f32_32x32x16_bf16 v[50:65], v[208:211], v[74:77], v[50:65]
	ds_read_b64_tr_b16 v[200:201], v227 offset:13824
	ds_read_b64_tr_b16 v[202:203], v227 offset:14400
	ds_read_b64_tr_b16 v[204:205], v227 offset:13888
	ds_read_b64_tr_b16 v[206:207], v227 offset:14464
	v_exp_f32_e32 v100, v100
	v_exp_f32_e32 v101, v101
	v_add_f32_e32 v219, v219, v100
	v_add_f32_e32 v220, v220, v101
	v_cvt_pk_bf16_f32 v99, v100, v101
	v_mfma_f32_32x32x16_bf16 v[34:49], v[212:215], v[74:77], v[34:49]
	v_exp_f32_e32 v102, v102
	v_exp_f32_e32 v103, v103
	v_add_f32_e32 v178, v178, v102
	v_add_f32_e32 v218, v218, v103
	v_cvt_pk_bf16_f32 v100, v102, v103
	v_mfma_f32_32x32x16_bf16 v[18:33], v[208:211], v[90:93], v[18:33]
	v_exp_f32_e32 v104, v104
	v_exp_f32_e32 v105, v105
	v_add_f32_e32 v219, v219, v104
	v_add_f32_e32 v220, v220, v105
	v_cvt_pk_bf16_f32 v101, v104, v105
	v_mfma_f32_32x32x16_bf16 v[2:17], v[212:215], v[90:93], v[2:17]
	v_exp_f32_e32 v114, v114
	v_exp_f32_e32 v115, v115
	v_add_f32_e32 v179, v179, v114
	v_add_f32_e32 v221, v221, v115
	v_cvt_pk_bf16_f32 v114, v114, v115
	s_waitcnt lgkmcnt(4)
	v_mfma_f32_32x32x16_bf16 v[66:81], v[184:187], v[130:133], 0
	ds_read_b64_tr_b16 v[208:209], v227 offset:16128
	ds_read_b64_tr_b16 v[210:211], v227 offset:16704
	ds_read_b64_tr_b16 v[212:213], v227 offset:16192
	ds_read_b64_tr_b16 v[214:215], v227 offset:16768
	v_exp_f32_e32 v116, v116
	v_exp_f32_e32 v117, v117
	v_add_f32_e32 v222, v222, v116
	v_add_f32_e32 v223, v223, v117
	v_cvt_pk_bf16_f32 v115, v116, v117
	v_mfma_f32_32x32x16_bf16 v[66:81], v[188:191], v[134:137], v[66:81]
	v_exp_f32_e32 v118, v118
	v_exp_f32_e32 v119, v119
	v_add_f32_e32 v179, v179, v118
	v_add_f32_e32 v221, v221, v119
	v_cvt_pk_bf16_f32 v116, v118, v119
	v_mfma_f32_32x32x16_bf16 v[66:81], v[192:195], v[146:149], v[66:81]
	v_exp_f32_e32 v120, v120
	v_exp_f32_e32 v121, v121
	v_add_f32_e32 v222, v222, v120
	v_add_f32_e32 v223, v223, v121
	v_cvt_pk_bf16_f32 v117, v120, v121
	v_mfma_f32_32x32x16_bf16 v[66:81], v[196:199], v[150:153], v[66:81]
	v_exp_f32_e32 v106, v106
	v_exp_f32_e32 v107, v107
	v_add_f32_e32 v178, v178, v106
	v_add_f32_e32 v218, v218, v107
	v_cvt_pk_bf16_f32 v106, v106, v107
	s_waitcnt lgkmcnt(4)
	v_mfma_f32_32x32x16_bf16 v[50:65], v[200:203], v[98:101], v[50:65]
	v_exp_f32_e32 v108, v108
	v_exp_f32_e32 v109, v109
	v_add_f32_e32 v219, v219, v108
	v_add_f32_e32 v220, v220, v109
	v_cvt_pk_bf16_f32 v107, v108, v109
	v_mfma_f32_32x32x16_bf16 v[34:49], v[204:207], v[98:101], v[34:49]
	v_exp_f32_e32 v110, v110
	v_exp_f32_e32 v111, v111
	v_add_f32_e32 v178, v178, v110
	v_add_f32_e32 v218, v218, v111
	v_cvt_pk_bf16_f32 v108, v110, v111
	v_mfma_f32_32x32x16_bf16 v[18:33], v[200:203], v[114:117], v[18:33]
	v_exp_f32_e32 v112, v112
	v_exp_f32_e32 v113, v113
	v_add_f32_e32 v219, v219, v112
	v_add_f32_e32 v220, v220, v113
	v_cvt_pk_bf16_f32 v109, v112, v113
	v_mfma_f32_32x32x16_bf16 v[2:17], v[204:207], v[114:117], v[2:17]
	v_exp_f32_e32 v122, v122
	v_exp_f32_e32 v123, v123
	v_add_f32_e32 v179, v179, v122
	v_add_f32_e32 v221, v221, v123
	v_cvt_pk_bf16_f32 v122, v122, v123
	v_mfma_f32_32x32x16_bf16 v[82:97], v[184:187], v[154:157], 0
	v_exp_f32_e32 v124, v124
	v_exp_f32_e32 v125, v125
	v_add_f32_e32 v222, v222, v124
	v_add_f32_e32 v223, v223, v125
	v_cvt_pk_bf16_f32 v123, v124, v125
	v_mfma_f32_32x32x16_bf16 v[82:97], v[188:191], v[138:141], v[82:97]
	v_exp_f32_e32 v126, v126
	v_exp_f32_e32 v127, v127
	v_add_f32_e32 v179, v179, v126
	v_add_f32_e32 v221, v221, v127
	v_cvt_pk_bf16_f32 v124, v126, v127
	v_mfma_f32_32x32x16_bf16 v[82:97], v[192:195], v[142:145], v[82:97]
	v_exp_f32_e32 v128, v128
	v_exp_f32_e32 v129, v129
	v_add_f32_e32 v222, v222, v128
	v_add_f32_e32 v223, v223, v129
	v_cvt_pk_bf16_f32 v125, v128, v129
	v_mfma_f32_32x32x16_bf16 v[82:97], v[196:199], v[158:161], v[82:97]
	s_waitcnt lgkmcnt(0)
	v_mfma_f32_32x32x16_bf16 v[50:65], v[208:211], v[106:109], v[50:65]
	v_mfma_f32_32x32x16_bf16 v[34:49], v[212:215], v[106:109], v[34:49]
	v_mfma_f32_32x32x16_bf16 v[18:33], v[208:211], v[122:125], v[18:33]
	v_mfma_f32_32x32x16_bf16 v[2:17], v[212:215], v[122:125], v[2:17]
	v_add_f32_e32 v178, v178, v218
	v_add_f32_e32 v219, v219, v220
	v_add_f32_e32 v179, v179, v221
	v_add_f32_e32 v222, v222, v223
	v_add_f32_e32 v178, v178, v219
	v_add_f32_e32 v179, v179, v222
	s_branch .LBB0_299
